# B0-fragment ds_reads of P1/P5 moved into L8/L4 (Bx regs free there) with covering vmcnt(10) in L7/L3, all 4 GEMM loops
# speedup vs baseline: 1.0148x; 1.0071x over previous
.LBB0_383:
	s_ashr_i32 s49, s48, 31
	s_lshl_b64 s[52:53], s[48:49], 19
	s_add_u32 s52, s10, s52
	s_addc_u32 s53, s11, s53
	s_and_b64 s[42:43], s[42:43], exec
	s_cselect_b32 s49, s53, s55
	s_cselect_b32 s66, s52, s54
	s_add_u32 s42, s56, 0x30080
	s_addc_u32 s43, s57, 0
	s_add_u32 s67, s54, 0x100
	v_mov_b32_e32 v16, 0
	s_addc_u32 s68, s55, 0
	s_mov_b32 s69, -2
	v_mov_b32_e32 v17, v16
	v_mov_b32_e32 v18, v16
	v_mov_b32_e32 v19, v16
	v_mov_b32_e32 v20, v16
	v_mov_b32_e32 v21, v16
	v_mov_b32_e32 v22, v16
	v_mov_b32_e32 v23, v16
	v_mov_b32_e32 v56, v16
	v_mov_b32_e32 v57, v16
	v_mov_b32_e32 v58, v16
	v_mov_b32_e32 v59, v16
	v_mov_b32_e32 v60, v16
	v_mov_b32_e32 v61, v16
	v_mov_b32_e32 v62, v16
	v_mov_b32_e32 v63, v16
	v_mov_b32_e32 v72, v16
	v_mov_b32_e32 v73, v16
	v_mov_b32_e32 v74, v16
	v_mov_b32_e32 v75, v16
	v_mov_b32_e32 v76, v16
	v_mov_b32_e32 v77, v16
	v_mov_b32_e32 v78, v16
	v_mov_b32_e32 v79, v16
	v_mov_b32_e32 v24, v16
	v_mov_b32_e32 v25, v16
	v_mov_b32_e32 v26, v16
	v_mov_b32_e32 v27, v16
	v_mov_b32_e32 v28, v16
	v_mov_b32_e32 v29, v16
	v_mov_b32_e32 v30, v16
	v_mov_b32_e32 v31, v16
	v_mov_b32_e32 v64, v16
	v_mov_b32_e32 v65, v16
	v_mov_b32_e32 v66, v16
	v_mov_b32_e32 v67, v16
	v_mov_b32_e32 v68, v16
	v_mov_b32_e32 v69, v16
	v_mov_b32_e32 v70, v16
	v_mov_b32_e32 v71, v16
	v_mov_b32_e32 v80, v16
	v_mov_b32_e32 v81, v16
	v_mov_b32_e32 v82, v16
	v_mov_b32_e32 v83, v16
	v_mov_b32_e32 v84, v16
	v_mov_b32_e32 v85, v16
	v_mov_b32_e32 v86, v16
	v_mov_b32_e32 v87, v16
	v_mov_b32_e32 v88, v16
	v_mov_b32_e32 v89, v16
	v_mov_b32_e32 v90, v16
	v_mov_b32_e32 v91, v16
	v_mov_b32_e32 v92, v16
	v_mov_b32_e32 v93, v16
	v_mov_b32_e32 v94, v16
	v_mov_b32_e32 v95, v16
	v_mov_b32_e32 v106, v16
	v_mov_b32_e32 v107, v16
	v_mov_b32_e32 v108, v16
	v_mov_b32_e32 v109, v16
	v_mov_b32_e32 v110, v16
	v_mov_b32_e32 v111, v16
	v_mov_b32_e32 v112, v16
	v_mov_b32_e32 v113, v16
	v_mov_b32_e32 v122, v16
	v_mov_b32_e32 v123, v16
	v_mov_b32_e32 v124, v16
	v_mov_b32_e32 v125, v16
	v_mov_b32_e32 v126, v16
	v_mov_b32_e32 v127, v16
	v_mov_b32_e32 v128, v16
	v_mov_b32_e32 v129, v16
	v_mov_b32_e32 v98, v16
	v_mov_b32_e32 v99, v16
	v_mov_b32_e32 v100, v16
	v_mov_b32_e32 v101, v16
	v_mov_b32_e32 v102, v16
	v_mov_b32_e32 v103, v16
	v_mov_b32_e32 v104, v16
	v_mov_b32_e32 v105, v16
	v_mov_b32_e32 v114, v16
	v_mov_b32_e32 v115, v16
	v_mov_b32_e32 v116, v16
	v_mov_b32_e32 v117, v16
	v_mov_b32_e32 v118, v16
	v_mov_b32_e32 v119, v16
	v_mov_b32_e32 v120, v16
	v_mov_b32_e32 v121, v16
	v_mov_b32_e32 v130, v16
	v_mov_b32_e32 v131, v16
	v_mov_b32_e32 v132, v16
	v_mov_b32_e32 v133, v16
	v_mov_b32_e32 v134, v16
	v_mov_b32_e32 v135, v16
	v_mov_b32_e32 v136, v16
	v_mov_b32_e32 v137, v16
	v_add_u32_e32 v96, 0x10000, v157
	ds_read_b128 v[160:163], v96
	ds_read_b128 v[164:167], v96 offset:1024
	ds_read_b128 v[168:171], v96 offset:2048
	ds_read_b128 v[172:175], v96 offset:3072
.LBB0_384:
	s_add_u32 s54, s42, 0xfffd0080
	s_addc_u32 s55, s43, -1
	s_add_i32 s70, 0, 0x10000
	v_add_u32_e32 v96, s70, v157
	s_cmp_eq_u32 s69, 12
	s_cselect_b32 s57, s51, s55
	s_cselect_b32 s56, s50, s54
	s_cselect_b32 s55, s49, s68
	s_cselect_b32 s54, s66, s67
	s_add_i32 m0, s28, 0xc000
	ds_read_b128 v[182:185], v159
	ds_read_b128 v[186:189], v159 offset:1024
	ds_read_b128 v[190:193], v159 offset:2048
	ds_read_b128 v[194:197], v159 offset:3072
	ds_read_b128 v[198:201], v159 offset:4096
	ds_read_b128 v[224:227], v159 offset:5120
	global_load_lds_dwordx4 v150, s[42:43]
	s_add_i32 m0, s28, 0xe000
	s_mov_b64 exec, s[98:99]
	global_load_lds_dwordx4 v152, s[42:43]
	s_mov_b64 exec, -1
	s_setprio 1
	s_barrier
	s_waitcnt lgkmcnt(0)
	v_mfma_f32_16x16x32_bf16 v[134:137], v[160:163], v[182:185], v[134:137]
	v_mfma_f32_16x16x32_bf16 v[130:133], v[168:171], v[182:185], v[130:133]
	v_mfma_f32_16x16x32_bf16 v[118:121], v[160:163], v[190:193], v[118:121]
	v_mfma_f32_16x16x32_bf16 v[114:117], v[168:171], v[190:193], v[114:117]
	v_mfma_f32_16x16x32_bf16 v[102:105], v[160:163], v[198:201], v[102:105]
	v_mfma_f32_16x16x32_bf16 v[98:101], v[168:171], v[198:201], v[98:101]
	v_mfma_f32_16x16x32_bf16 v[134:137], v[164:167], v[186:189], v[134:137]
	v_mfma_f32_16x16x32_bf16 v[130:133], v[172:175], v[186:189], v[130:133]
	v_mfma_f32_16x16x32_bf16 v[118:121], v[164:167], v[194:197], v[118:121]
	v_mfma_f32_16x16x32_bf16 v[114:117], v[172:175], v[194:197], v[114:117]
	v_mfma_f32_16x16x32_bf16 v[102:105], v[164:167], v[224:227], v[102:105]
	v_mfma_f32_16x16x32_bf16 v[98:101], v[172:175], v[224:227], v[98:101]
	s_barrier
	s_setprio 0
	s_add_i32 s72, 0, 0x14000
	s_add_i32 s70, s70, s18
	v_add_u32_e32 v96, s72, v157
	v_lshl_add_u64 v[154:155], s[54:55], 0, v[142:143]
	s_mov_b32 m0, s70
	ds_read_b128 v[228:231], v96
	ds_read_b128 v[232:235], v96 offset:1024
	ds_read_b128 v[236:239], v96 offset:2048
	ds_read_b128 v[240:243], v96 offset:3072
	global_load_lds_dwordx4 v142, s[54:55]
	v_lshl_add_u64 v[176:177], s[54:55], 0, v[138:139]
	s_add_i32 m0, s70, 0x2000
	s_nop 0
	global_load_lds_dwordx4 v138, s[54:55]
	s_setprio 1
	s_barrier
	s_waitcnt lgkmcnt(0)
	v_mfma_f32_16x16x32_bf16 v[126:129], v[228:231], v[182:185], v[126:129]
	v_mfma_f32_16x16x32_bf16 v[122:125], v[236:239], v[182:185], v[122:125]
	v_mfma_f32_16x16x32_bf16 v[110:113], v[228:231], v[190:193], v[110:113]
	s_mov_b32 m0, s28
	v_mfma_f32_16x16x32_bf16 v[106:109], v[236:239], v[190:193], v[106:109]
	v_lshl_add_u64 v[202:203], s[56:57], 0, v[144:145]
	v_mfma_f32_16x16x32_bf16 v[92:95], v[228:231], v[198:201], v[92:95]
	v_mfma_f32_16x16x32_bf16 v[88:91], v[236:239], v[198:201], v[88:91]
	v_mfma_f32_16x16x32_bf16 v[126:129], v[232:235], v[186:189], v[126:129]
	v_mfma_f32_16x16x32_bf16 v[122:125], v[240:243], v[186:189], v[122:125]
	v_mfma_f32_16x16x32_bf16 v[110:113], v[232:235], v[194:197], v[110:113]
	v_mfma_f32_16x16x32_bf16 v[106:109], v[240:243], v[194:197], v[106:109]
	v_mfma_f32_16x16x32_bf16 v[92:95], v[232:235], v[224:227], v[92:95]
	v_mfma_f32_16x16x32_bf16 v[88:91], v[240:243], v[224:227], v[88:91]
	s_barrier
	s_setprio 0
	ds_read_b128 v[182:185], v159 offset:16384
	ds_read_b128 v[186:189], v159 offset:17408
	ds_read_b128 v[190:193], v159 offset:18432
	ds_read_b128 v[194:197], v159 offset:19456
	ds_read_b128 v[198:201], v159 offset:20480
	ds_read_b128 v[224:227], v159 offset:21504
	global_load_lds_dwordx4 v144, s[56:57]
	v_lshl_add_u64 v[244:245], s[56:57], 0, v[140:141]
	s_mov_b32 m0, s37
	s_mov_b64 exec, s[98:99]
	global_load_lds_dwordx4 v140, s[56:57]
	s_mov_b64 exec, -1
	s_waitcnt vmcnt(10)
	s_setprio 1
	s_barrier
	s_waitcnt lgkmcnt(0)
	v_mfma_f32_16x16x32_bf16 v[84:87], v[160:163], v[182:185], v[84:87]
	v_mfma_f32_16x16x32_bf16 v[80:83], v[168:171], v[182:185], v[80:83]
	v_mfma_f32_16x16x32_bf16 v[68:71], v[160:163], v[190:193], v[68:71]
	v_mfma_f32_16x16x32_bf16 v[64:67], v[168:171], v[190:193], v[64:67]
	v_mfma_f32_16x16x32_bf16 v[28:31], v[160:163], v[198:201], v[28:31]
	v_mfma_f32_16x16x32_bf16 v[24:27], v[168:171], v[198:201], v[24:27]
	v_mfma_f32_16x16x32_bf16 v[84:87], v[164:167], v[186:189], v[84:87]
	v_mfma_f32_16x16x32_bf16 v[80:83], v[172:175], v[186:189], v[80:83]
	v_mfma_f32_16x16x32_bf16 v[68:71], v[164:167], v[194:197], v[68:71]
	v_mfma_f32_16x16x32_bf16 v[64:67], v[172:175], v[194:197], v[64:67]
	v_mfma_f32_16x16x32_bf16 v[28:31], v[164:167], v[224:227], v[28:31]
	v_mfma_f32_16x16x32_bf16 v[24:27], v[172:175], v[224:227], v[24:27]
	s_barrier
	s_setprio 0
	v_add_u32_e32 v96, 0x18000, v157
	ds_read_b128 v[160:163], v96
	ds_read_b128 v[164:167], v96 offset:1024
	ds_read_b128 v[168:171], v96 offset:2048
	ds_read_b128 v[172:175], v96 offset:3072
	s_add_u32 s70, s54, 0x40000
	s_addc_u32 s71, s55, 0
	s_add_i32 s72, s72, s18
	s_mov_b32 m0, s72
	s_nop 0
	global_load_lds_dwordx4 v142, s[70:71]
	s_add_i32 m0, s72, 0x2000
	s_nop 0
	global_load_lds_dwordx4 v138, s[70:71]
	s_waitcnt vmcnt(6)
	s_setprio 1
	s_barrier
	v_mfma_f32_16x16x32_bf16 v[76:79], v[228:231], v[182:185], v[76:79]
	v_mfma_f32_16x16x32_bf16 v[72:75], v[236:239], v[182:185], v[72:75]
	v_mfma_f32_16x16x32_bf16 v[60:63], v[228:231], v[190:193], v[60:63]
	s_add_i32 s70, 0, 0x18000
	v_mfma_f32_16x16x32_bf16 v[56:59], v[236:239], v[190:193], v[56:59]
	v_add_u32_e32 v96, s70, v157
	v_mfma_f32_16x16x32_bf16 v[20:23], v[228:231], v[198:201], v[20:23]
	v_mfma_f32_16x16x32_bf16 v[16:19], v[236:239], v[198:201], v[16:19]
	v_mfma_f32_16x16x32_bf16 v[76:79], v[232:235], v[186:189], v[76:79]
	v_mfma_f32_16x16x32_bf16 v[72:75], v[240:243], v[186:189], v[72:75]
	v_mfma_f32_16x16x32_bf16 v[60:63], v[232:235], v[194:197], v[60:63]
	v_mfma_f32_16x16x32_bf16 v[56:59], v[240:243], v[194:197], v[56:59]
	v_mfma_f32_16x16x32_bf16 v[20:23], v[232:235], v[224:227], v[20:23]
	v_mfma_f32_16x16x32_bf16 v[16:19], v[240:243], v[224:227], v[16:19]
	s_barrier
	s_setprio 0
	s_add_u32 s56, s56, 0x30000
	s_addc_u32 s57, s57, 0
	s_mov_b32 m0, s58
	ds_read_b128 v[182:185], v159 offset:32768
	ds_read_b128 v[186:189], v159 offset:33792
	ds_read_b128 v[190:193], v159 offset:34816
	ds_read_b128 v[194:197], v159 offset:35840
	ds_read_b128 v[198:201], v159 offset:36864
	ds_read_b128 v[224:227], v159 offset:37888
	global_load_lds_dwordx4 v144, s[56:57]
	s_mov_b32 m0, s59
	s_mov_b64 exec, s[98:99]
	global_load_lds_dwordx4 v140, s[56:57]
	s_mov_b64 exec, -1
	s_setprio 1
	s_barrier
	s_waitcnt lgkmcnt(0)
	v_mfma_f32_16x16x32_bf16 v[134:137], v[160:163], v[182:185], v[134:137]
	v_mfma_f32_16x16x32_bf16 v[130:133], v[168:171], v[182:185], v[130:133]
	v_mfma_f32_16x16x32_bf16 v[118:121], v[160:163], v[190:193], v[118:121]
	v_mfma_f32_16x16x32_bf16 v[114:117], v[168:171], v[190:193], v[114:117]
	v_mfma_f32_16x16x32_bf16 v[102:105], v[160:163], v[198:201], v[102:105]
	v_mfma_f32_16x16x32_bf16 v[98:101], v[168:171], v[198:201], v[98:101]
	v_mfma_f32_16x16x32_bf16 v[134:137], v[164:167], v[186:189], v[134:137]
	v_mfma_f32_16x16x32_bf16 v[130:133], v[172:175], v[186:189], v[130:133]
	v_mfma_f32_16x16x32_bf16 v[118:121], v[164:167], v[194:197], v[118:121]
	v_mfma_f32_16x16x32_bf16 v[114:117], v[172:175], v[194:197], v[114:117]
	v_mfma_f32_16x16x32_bf16 v[102:105], v[164:167], v[224:227], v[102:105]
	v_mfma_f32_16x16x32_bf16 v[98:101], v[172:175], v[224:227], v[98:101]
	s_barrier
	s_setprio 0
	s_add_i32 s56, 0, 0x1c000
	s_add_i32 s57, s70, s18
	v_add_u32_e32 v96, s56, v157
	v_lshl_add_u64 v[154:155], v[154:155], 0, s[6:7]
	s_mov_b32 m0, s57
	ds_read_b128 v[228:231], v96
	ds_read_b128 v[232:235], v96 offset:1024
	ds_read_b128 v[236:239], v96 offset:2048
	ds_read_b128 v[240:243], v96 offset:3072
	global_load_lds_dwordx4 v[154:155], off
	v_lshl_add_u64 v[154:155], v[176:177], 0, s[6:7]
	s_add_i32 m0, s57, 0x2000
	s_nop 0
	global_load_lds_dwordx4 v[154:155], off
	s_setprio 1
	s_barrier
	s_waitcnt lgkmcnt(0)
	v_mfma_f32_16x16x32_bf16 v[126:129], v[228:231], v[182:185], v[126:129]
	v_mfma_f32_16x16x32_bf16 v[122:125], v[236:239], v[182:185], v[122:125]
	v_mfma_f32_16x16x32_bf16 v[110:113], v[228:231], v[190:193], v[110:113]
	s_mov_b32 m0, s60
	v_mfma_f32_16x16x32_bf16 v[106:109], v[236:239], v[190:193], v[106:109]
	v_lshl_add_u64 v[154:155], v[202:203], 0, s[6:7]
	v_mfma_f32_16x16x32_bf16 v[92:95], v[228:231], v[198:201], v[92:95]
	v_mfma_f32_16x16x32_bf16 v[88:91], v[236:239], v[198:201], v[88:91]
	v_mfma_f32_16x16x32_bf16 v[126:129], v[232:235], v[186:189], v[126:129]
	v_mfma_f32_16x16x32_bf16 v[122:125], v[240:243], v[186:189], v[122:125]
	v_mfma_f32_16x16x32_bf16 v[110:113], v[232:235], v[194:197], v[110:113]
	v_mfma_f32_16x16x32_bf16 v[106:109], v[240:243], v[194:197], v[106:109]
	v_mfma_f32_16x16x32_bf16 v[92:95], v[232:235], v[224:227], v[92:95]
	v_mfma_f32_16x16x32_bf16 v[88:91], v[240:243], v[224:227], v[88:91]
	s_barrier
	s_setprio 0
	ds_read_b128 v[182:185], v159 offset:49152
	ds_read_b128 v[186:189], v159 offset:50176
	ds_read_b128 v[190:193], v159 offset:51200
	ds_read_b128 v[194:197], v159 offset:52224
	ds_read_b128 v[198:201], v159 offset:53248
	ds_read_b128 v[224:227], v159 offset:54272
	global_load_lds_dwordx4 v[154:155], off
	v_lshl_add_u64 v[154:155], v[244:245], 0, s[6:7]
	s_mov_b32 m0, s61
	s_mov_b64 exec, s[98:99]
	global_load_lds_dwordx4 v[154:155], off
	s_mov_b64 exec, -1
	s_waitcnt vmcnt(10)
	s_setprio 1
	s_barrier
	s_waitcnt lgkmcnt(0)
	v_mfma_f32_16x16x32_bf16 v[84:87], v[160:163], v[182:185], v[84:87]
	v_mfma_f32_16x16x32_bf16 v[80:83], v[168:171], v[182:185], v[80:83]
	v_mfma_f32_16x16x32_bf16 v[68:71], v[160:163], v[190:193], v[68:71]
	v_mfma_f32_16x16x32_bf16 v[64:67], v[168:171], v[190:193], v[64:67]
	v_mfma_f32_16x16x32_bf16 v[28:31], v[160:163], v[198:201], v[28:31]
	v_mfma_f32_16x16x32_bf16 v[24:27], v[168:171], v[198:201], v[24:27]
	v_mfma_f32_16x16x32_bf16 v[84:87], v[164:167], v[186:189], v[84:87]
	v_mfma_f32_16x16x32_bf16 v[80:83], v[172:175], v[186:189], v[80:83]
	v_mfma_f32_16x16x32_bf16 v[68:71], v[164:167], v[194:197], v[68:71]
	v_mfma_f32_16x16x32_bf16 v[64:67], v[172:175], v[194:197], v[64:67]
	v_mfma_f32_16x16x32_bf16 v[28:31], v[164:167], v[224:227], v[28:31]
	v_mfma_f32_16x16x32_bf16 v[24:27], v[172:175], v[224:227], v[24:27]
	s_barrier
	s_setprio 0
	v_add_u32_e32 v96, 0x10000, v157
	ds_read_b128 v[160:163], v96
	ds_read_b128 v[164:167], v96 offset:1024
	ds_read_b128 v[168:171], v96 offset:2048
	ds_read_b128 v[172:175], v96 offset:3072
	s_add_u32 s54, s54, 0x40080
	s_addc_u32 s55, s55, 0
	s_add_i32 s56, s56, s18
	s_mov_b32 m0, s56
	s_nop 0
	global_load_lds_dwordx4 v142, s[54:55]
	s_add_i32 m0, s56, 0x2000
	s_nop 0
	global_load_lds_dwordx4 v138, s[54:55]
	s_waitcnt vmcnt(6)
	s_setprio 1
	s_barrier
	v_mfma_f32_16x16x32_bf16 v[76:79], v[228:231], v[182:185], v[76:79]
	v_mfma_f32_16x16x32_bf16 v[72:75], v[236:239], v[182:185], v[72:75]
	v_mfma_f32_16x16x32_bf16 v[60:63], v[228:231], v[190:193], v[60:63]
	s_add_i32 s69, s69, 2
	v_mfma_f32_16x16x32_bf16 v[56:59], v[236:239], v[190:193], v[56:59]
	s_add_u32 s42, s42, 0x100
	v_mfma_f32_16x16x32_bf16 v[20:23], v[228:231], v[198:201], v[20:23]
	s_addc_u32 s43, s43, 0
	v_mfma_f32_16x16x32_bf16 v[16:19], v[236:239], v[198:201], v[16:19]
	s_add_u32 s67, s67, 0x100
	v_mfma_f32_16x16x32_bf16 v[76:79], v[232:235], v[186:189], v[76:79]
	s_addc_u32 s68, s68, 0
	v_mfma_f32_16x16x32_bf16 v[72:75], v[240:243], v[186:189], v[72:75]
	s_cmp_gt_u32 s69, 13
	v_mfma_f32_16x16x32_bf16 v[60:63], v[232:235], v[194:197], v[60:63]
	v_mfma_f32_16x16x32_bf16 v[56:59], v[240:243], v[194:197], v[56:59]
	v_mfma_f32_16x16x32_bf16 v[20:23], v[232:235], v[224:227], v[20:23]
	v_mfma_f32_16x16x32_bf16 v[16:19], v[240:243], v[224:227], v[16:19]
	s_barrier
	s_setprio 0
	s_cbranch_scc0 .LBB0_384
	s_waitcnt lgkmcnt(0)
	s_waitcnt vmcnt(0)
	v_add_f32_e32 v52, v52, v53
	v_add_f32_e32 v53, v54, v55
	v_add_f32_e32 v52, v52, v53
	v_mov_b32_e32 v53, v52
	s_nop 1
	v_permlane16_swap_b32_e32 v52, v53
	v_add_f32_e32 v52, v52, v53
	v_mov_b32_e32 v53, v52
	s_nop 1
	v_permlane32_swap_b32_e32 v52, v53
	v_add_f32_e32 v52, v52, v53
	v_fmamk_f32 v52, v52, 0x3a800000, v207
	s_mul_i32 s42, s65, 0xc0
	v_rsq_f32_e32 v52, v52
	v_add_f32_e32 v36, v36, v37
	v_add_f32_e32 v37, v38, v39
	s_add_i32 s42, s42, s19
	v_add_f32_e32 v44, v44, v45
	v_add_f32_e32 v45, v46, v47
	v_add_f32_e32 v36, v36, v37
	s_cmpk_lt_u32 s42, 0x2000
	v_add_f32_e32 v44, v44, v45
	v_mov_b32_e32 v37, v36
	v_lshl_or_b32 v154, s64, 8, v158
	s_cselect_b32 s43, 1, 2
	v_or_b32_e32 v160, s42, v156
	v_mov_b32_e32 v45, v44
	v_permlane16_swap_b32_e32 v36, v37
	v_add_f32_e32 v32, v32, v33
	v_add_f32_e32 v33, v34, v35
	v_mov_b64_e32 v[34:35], s[46:47]
	v_mov_b32_e32 v96, s43
	v_permlane16_swap_b32_e32 v44, v45
	v_add_f32_e32 v38, v36, v37
	v_add_f32_e32 v36, v40, v41
	v_add_f32_e32 v37, v42, v43
	v_ashrrev_i32_e32 v155, 31, v154
	v_mad_i64_i32 v[34:35], s[42:43], v160, s25, v[34:35]
	v_pk_fma_f32 v[42:43], v[136:137], v[52:53], v[6:7] op_sel_hi:[1,0,1]
	v_pk_fma_f32 v[40:41], v[134:135], v[52:53], v[4:5] op_sel_hi:[1,0,1]
	v_add_f32_e32 v46, v44, v45
	v_add_f32_e32 v44, v48, v49
	v_add_f32_e32 v45, v50, v51
	v_lshl_add_u64 v[34:35], v[154:155], 1, v[34:35]
	v_pk_fma_f32 v[48:49], v[132:133], v[52:53], v[2:3] op_sel_hi:[1,0,1]
	v_pk_fma_f32 v[50:51], v[130:131], v[52:53], v[0:1] op_sel_hi:[1,0,1]
	v_cvt_pk_bf16_f32 v40, v40, v41
	v_cvt_pk_bf16_f32 v41, v42, v43
	v_add_f32_e32 v44, v44, v45
	v_cvt_pk_bf16_f32 v42, v50, v51
	v_cvt_pk_bf16_f32 v43, v48, v49
	v_add_f32_e32 v36, v36, v37
	v_add_f32_e32 v32, v32, v33
	global_store_dwordx4 v[34:35], v[40:43], off
	v_cmp_lt_i32_e32 vcc, s23, v160
	v_mov_b32_e32 v45, v44
	v_pk_fma_f32 v[42:43], v[128:129], v[52:53], v[14:15] op_sel_hi:[1,0,1]
	v_pk_fma_f32 v[40:41], v[126:127], v[52:53], v[12:13] op_sel_hi:[1,0,1]
	v_mov_b32_e32 v37, v36
	v_mov_b32_e32 v33, v32
	v_pk_fma_f32 v[48:49], v[124:125], v[52:53], v[10:11] op_sel_hi:[1,0,1]
	v_pk_fma_f32 v[50:51], v[122:123], v[52:53], v[8:9] op_sel_hi:[1,0,1]
	v_cvt_pk_bf16_f32 v40, v40, v41
	v_cvt_pk_bf16_f32 v41, v42, v43
	v_cndmask_b32_e32 v96, 0, v96, vcc
	v_cvt_pk_bf16_f32 v42, v50, v51
	v_cvt_pk_bf16_f32 v43, v48, v49
	global_store_dwordx4 v[34:35], v[40:43], off offset:256
	v_add_u32_e32 v34, 16, v160
	v_permlane16_swap_b32_e32 v44, v45
	v_permlane16_swap_b32_e32 v36, v37
	v_permlane16_swap_b32_e32 v32, v33
	v_cmp_gt_u32_e32 vcc, s24, v34
	v_add_f32_e32 v44, v44, v45
	v_add_f32_e32 v36, v36, v37
	v_add_f32_e32 v32, v32, v33
	v_cndmask_b32_e64 v35, 2, 1, vcc
	v_cmp_lt_i32_e32 vcc, s26, v160
	v_mov_b32_e32 v47, v46
	v_mov_b32_e32 v45, v44
	v_mov_b32_e32 v39, v38
	v_mov_b32_e32 v37, v36
	v_mov_b32_e32 v33, v32
	v_cndmask_b32_e32 v35, 0, v35, vcc
	v_permlane32_swap_b32_e32 v46, v47
	v_permlane32_swap_b32_e32 v44, v45
	v_permlane32_swap_b32_e32 v38, v39
	v_permlane32_swap_b32_e32 v36, v37
	v_permlane32_swap_b32_e32 v32, v33
	v_cmp_ne_u32_e32 vcc, v35, v96
	s_and_saveexec_b64 s[42:43], vcc
	s_cbranch_execz .LBB0_387
	v_mul_u32_u24_e32 v0, 0x7600, v35
	v_lshlrev_b32_e32 v96, 2, v0
	v_lshl_add_u64 v[0:1], s[44:45], 0, v[96:97]
	v_lshl_add_u64 v[12:13], v[154:155], 2, v[0:1]
	global_load_dwordx4 v[0:3], v[12:13], off offset:16
	global_load_dwordx4 v[4:7], v[12:13], off
	global_load_dwordx4 v[8:11], v[12:13], off offset:528
	s_nop 0
	global_load_dwordx4 v[12:15], v[12:13], off offset:512
	v_mov_b32_e32 v96, v35

.LBB0_464:
	s_ashr_i32 s51, s50, 31
	s_lshl_b64 s[54:55], s[50:51], 19
	s_add_u32 s54, s10, s54
	s_addc_u32 s55, s11, s55
	s_and_b64 s[42:43], s[42:43], exec
	s_cselect_b32 s51, s55, s59
	s_cselect_b32 s68, s54, s58
	s_add_u32 s42, s60, 0x30080
	s_addc_u32 s43, s61, 0
	s_add_u32 s69, s58, 0x100
	v_mov_b32_e32 v16, 0
	s_addc_u32 s70, s59, 0
	s_mov_b32 s71, -2
	v_mov_b32_e32 v17, v16
	v_mov_b32_e32 v18, v16
	v_mov_b32_e32 v19, v16
	v_mov_b32_e32 v20, v16
	v_mov_b32_e32 v21, v16
	v_mov_b32_e32 v22, v16
	v_mov_b32_e32 v23, v16
	v_mov_b32_e32 v32, v16
	v_mov_b32_e32 v33, v16
	v_mov_b32_e32 v34, v16
	v_mov_b32_e32 v35, v16
	v_mov_b32_e32 v36, v16
	v_mov_b32_e32 v37, v16
	v_mov_b32_e32 v38, v16
	v_mov_b32_e32 v39, v16
	v_mov_b32_e32 v48, v16
	v_mov_b32_e32 v49, v16
	v_mov_b32_e32 v50, v16
	v_mov_b32_e32 v51, v16
	v_mov_b32_e32 v52, v16
	v_mov_b32_e32 v53, v16
	v_mov_b32_e32 v54, v16
	v_mov_b32_e32 v55, v16
	v_mov_b32_e32 v24, v16
	v_mov_b32_e32 v25, v16
	v_mov_b32_e32 v26, v16
	v_mov_b32_e32 v27, v16
	v_mov_b32_e32 v28, v16
	v_mov_b32_e32 v29, v16
	v_mov_b32_e32 v30, v16
	v_mov_b32_e32 v31, v16
	v_mov_b32_e32 v40, v16
	v_mov_b32_e32 v41, v16
	v_mov_b32_e32 v42, v16
	v_mov_b32_e32 v43, v16
	v_mov_b32_e32 v44, v16
	v_mov_b32_e32 v45, v16
	v_mov_b32_e32 v46, v16
	v_mov_b32_e32 v47, v16
	v_mov_b32_e32 v56, v16
	v_mov_b32_e32 v57, v16
	v_mov_b32_e32 v58, v16
	v_mov_b32_e32 v59, v16
	v_mov_b32_e32 v60, v16
	v_mov_b32_e32 v61, v16
	v_mov_b32_e32 v62, v16
	v_mov_b32_e32 v63, v16
	v_mov_b32_e32 v64, v16
	v_mov_b32_e32 v65, v16
	v_mov_b32_e32 v66, v16
	v_mov_b32_e32 v67, v16
	v_mov_b32_e32 v68, v16
	v_mov_b32_e32 v69, v16
	v_mov_b32_e32 v70, v16
	v_mov_b32_e32 v71, v16
	v_mov_b32_e32 v80, v16
	v_mov_b32_e32 v81, v16
	v_mov_b32_e32 v82, v16
	v_mov_b32_e32 v83, v16
	v_mov_b32_e32 v84, v16
	v_mov_b32_e32 v85, v16
	v_mov_b32_e32 v86, v16
	v_mov_b32_e32 v87, v16
	v_mov_b32_e32 v98, v16
	v_mov_b32_e32 v99, v16
	v_mov_b32_e32 v100, v16
	v_mov_b32_e32 v101, v16
	v_mov_b32_e32 v110, v16
	v_mov_b32_e32 v111, v16
	v_mov_b32_e32 v112, v16
	v_mov_b32_e32 v113, v16
	v_mov_b32_e32 v72, v16
	v_mov_b32_e32 v73, v16
	v_mov_b32_e32 v74, v16
	v_mov_b32_e32 v75, v16
	v_mov_b32_e32 v76, v16
	v_mov_b32_e32 v77, v16
	v_mov_b32_e32 v78, v16
	v_mov_b32_e32 v79, v16
	v_mov_b32_e32 v88, v16
	v_mov_b32_e32 v89, v16
	v_mov_b32_e32 v90, v16
	v_mov_b32_e32 v91, v16
	v_mov_b32_e32 v92, v16
	v_mov_b32_e32 v93, v16
	v_mov_b32_e32 v94, v16
	v_mov_b32_e32 v95, v16
	v_mov_b32_e32 v130, v16
	v_mov_b32_e32 v131, v16
	v_mov_b32_e32 v132, v16
	v_mov_b32_e32 v133, v16
	v_mov_b32_e32 v134, v16
	v_mov_b32_e32 v135, v16
	v_mov_b32_e32 v136, v16
	v_mov_b32_e32 v137, v16
	v_add_u32_e32 v96, 0x10000, v163
	ds_read_b128 v[154:157], v96
	ds_read_b128 v[170:173], v96 offset:1024
	ds_read_b128 v[174:177], v96 offset:2048
	ds_read_b128 v[182:185], v96 offset:3072
.LBB0_465:
	s_add_u32 s58, s42, 0xfffd0080
	s_addc_u32 s59, s43, -1
	s_add_i32 s72, 0, 0x10000
	v_add_u32_e32 v96, s72, v163
	s_cmp_eq_u32 s71, 12
	s_cselect_b32 s61, s53, s59
	s_cselect_b32 s60, s52, s58
	s_cselect_b32 s59, s51, s70
	s_cselect_b32 s58, s68, s69
	s_add_i32 m0, s27, 0xc000
	ds_read_b128 v[186:189], v168
	ds_read_b128 v[190:193], v168 offset:1024
	ds_read_b128 v[194:197], v168 offset:2048
	ds_read_b128 v[198:201], v168 offset:3072
	ds_read_b128 v[224:227], v168 offset:4096
	ds_read_b128 v[228:231], v168 offset:5120
	global_load_lds_dwordx4 v150, s[42:43]
	s_add_i32 m0, s27, 0xe000
	s_mov_b64 exec, s[98:99]
	global_load_lds_dwordx4 v152, s[42:43]
	s_mov_b64 exec, -1
	s_setprio 1
	s_barrier
	s_waitcnt lgkmcnt(0)
	v_mfma_f32_16x16x32_bf16 v[134:137], v[154:157], v[186:189], v[134:137]
	v_mfma_f32_16x16x32_bf16 v[130:133], v[174:177], v[186:189], v[130:133]
	v_mfma_f32_16x16x32_bf16 v[92:95], v[154:157], v[194:197], v[92:95]
	v_mfma_f32_16x16x32_bf16 v[88:91], v[174:177], v[194:197], v[88:91]
	v_mfma_f32_16x16x32_bf16 v[76:79], v[154:157], v[224:227], v[76:79]
	v_mfma_f32_16x16x32_bf16 v[72:75], v[174:177], v[224:227], v[72:75]
	v_mfma_f32_16x16x32_bf16 v[134:137], v[170:173], v[190:193], v[134:137]
	v_mfma_f32_16x16x32_bf16 v[130:133], v[182:185], v[190:193], v[130:133]
	v_mfma_f32_16x16x32_bf16 v[92:95], v[170:173], v[198:201], v[92:95]
	v_mfma_f32_16x16x32_bf16 v[88:91], v[182:185], v[198:201], v[88:91]
	v_mfma_f32_16x16x32_bf16 v[76:79], v[170:173], v[228:231], v[76:79]
	v_mfma_f32_16x16x32_bf16 v[72:75], v[182:185], v[228:231], v[72:75]
	s_barrier
	s_setprio 0
	s_add_i32 s80, 0, 0x14000
	s_add_i32 s72, s72, s18
	v_add_u32_e32 v96, s80, v163
	v_lshl_add_u64 v[160:161], s[58:59], 0, v[140:141]
	s_mov_b32 m0, s72
	ds_read_b128 v[232:235], v96
	ds_read_b128 v[236:239], v96 offset:1024
	ds_read_b128 v[240:243], v96 offset:2048
	ds_read_b128 v[244:247], v96 offset:3072
	global_load_lds_dwordx4 v140, s[58:59]
	v_lshl_add_u64 v[164:165], s[58:59], 0, v[144:145]
	s_add_i32 m0, s72, 0x2000
	s_nop 0
	global_load_lds_dwordx4 v144, s[58:59]
	s_setprio 1
	s_barrier
	s_waitcnt lgkmcnt(0)
	v_mfma_f32_16x16x32_bf16 v[110:113], v[232:235], v[186:189], v[110:113]
	v_mfma_f32_16x16x32_bf16 v[98:101], v[240:243], v[186:189], v[98:101]
	v_mfma_f32_16x16x32_bf16 v[84:87], v[232:235], v[194:197], v[84:87]
	s_mov_b32 m0, s27
	v_mfma_f32_16x16x32_bf16 v[80:83], v[240:243], v[194:197], v[80:83]
	v_lshl_add_u64 v[202:203], s[60:61], 0, v[138:139]
	v_mfma_f32_16x16x32_bf16 v[68:71], v[232:235], v[224:227], v[68:71]
	v_mfma_f32_16x16x32_bf16 v[64:67], v[240:243], v[224:227], v[64:67]
	v_mfma_f32_16x16x32_bf16 v[110:113], v[236:239], v[190:193], v[110:113]
	v_mfma_f32_16x16x32_bf16 v[98:101], v[244:247], v[190:193], v[98:101]
	v_mfma_f32_16x16x32_bf16 v[84:87], v[236:239], v[198:201], v[84:87]
	v_mfma_f32_16x16x32_bf16 v[80:83], v[244:247], v[198:201], v[80:83]
	v_mfma_f32_16x16x32_bf16 v[68:71], v[236:239], v[228:231], v[68:71]
	v_mfma_f32_16x16x32_bf16 v[64:67], v[244:247], v[228:231], v[64:67]
	s_barrier
	s_setprio 0
	ds_read_b128 v[186:189], v168 offset:16384
	ds_read_b128 v[190:193], v168 offset:17408
	ds_read_b128 v[194:197], v168 offset:18432
	ds_read_b128 v[198:201], v168 offset:19456
	ds_read_b128 v[224:227], v168 offset:20480
	ds_read_b128 v[228:231], v168 offset:21504
	global_load_lds_dwordx4 v138, s[60:61]
	v_lshl_add_u64 v[248:249], s[60:61], 0, v[142:143]
	s_mov_b32 m0, s28
	s_mov_b64 exec, s[98:99]
	global_load_lds_dwordx4 v142, s[60:61]
	s_mov_b64 exec, -1
	s_waitcnt vmcnt(10)
	s_setprio 1
	s_barrier
	s_waitcnt lgkmcnt(0)
	v_mfma_f32_16x16x32_bf16 v[60:63], v[154:157], v[186:189], v[60:63]
	v_mfma_f32_16x16x32_bf16 v[56:59], v[174:177], v[186:189], v[56:59]
	v_mfma_f32_16x16x32_bf16 v[44:47], v[154:157], v[194:197], v[44:47]
	v_mfma_f32_16x16x32_bf16 v[40:43], v[174:177], v[194:197], v[40:43]
	v_mfma_f32_16x16x32_bf16 v[28:31], v[154:157], v[224:227], v[28:31]
	v_mfma_f32_16x16x32_bf16 v[24:27], v[174:177], v[224:227], v[24:27]
	v_mfma_f32_16x16x32_bf16 v[60:63], v[170:173], v[190:193], v[60:63]
	v_mfma_f32_16x16x32_bf16 v[56:59], v[182:185], v[190:193], v[56:59]
	v_mfma_f32_16x16x32_bf16 v[44:47], v[170:173], v[198:201], v[44:47]
	v_mfma_f32_16x16x32_bf16 v[40:43], v[182:185], v[198:201], v[40:43]
	v_mfma_f32_16x16x32_bf16 v[28:31], v[170:173], v[228:231], v[28:31]
	v_mfma_f32_16x16x32_bf16 v[24:27], v[182:185], v[228:231], v[24:27]
	s_barrier
	s_setprio 0
	v_add_u32_e32 v96, 0x18000, v163
	ds_read_b128 v[154:157], v96
	ds_read_b128 v[170:173], v96 offset:1024
	ds_read_b128 v[174:177], v96 offset:2048
	ds_read_b128 v[182:185], v96 offset:3072
	s_add_u32 s78, s58, 0x40000
	s_addc_u32 s79, s59, 0
	s_add_i32 s72, s80, s18
	s_mov_b32 m0, s72
	s_nop 0
	global_load_lds_dwordx4 v140, s[78:79]
	s_add_i32 m0, s72, 0x2000
	s_nop 0
	global_load_lds_dwordx4 v144, s[78:79]
	s_waitcnt vmcnt(6)
	s_setprio 1
	s_barrier
	v_mfma_f32_16x16x32_bf16 v[52:55], v[232:235], v[186:189], v[52:55]
	v_mfma_f32_16x16x32_bf16 v[48:51], v[240:243], v[186:189], v[48:51]
	v_mfma_f32_16x16x32_bf16 v[36:39], v[232:235], v[194:197], v[36:39]
	s_add_i32 s72, 0, 0x18000
	v_mfma_f32_16x16x32_bf16 v[32:35], v[240:243], v[194:197], v[32:35]
	v_add_u32_e32 v96, s72, v163
	v_mfma_f32_16x16x32_bf16 v[20:23], v[232:235], v[224:227], v[20:23]
	v_mfma_f32_16x16x32_bf16 v[16:19], v[240:243], v[224:227], v[16:19]
	v_mfma_f32_16x16x32_bf16 v[52:55], v[236:239], v[190:193], v[52:55]
	v_mfma_f32_16x16x32_bf16 v[48:51], v[244:247], v[190:193], v[48:51]
	v_mfma_f32_16x16x32_bf16 v[36:39], v[236:239], v[198:201], v[36:39]
	v_mfma_f32_16x16x32_bf16 v[32:35], v[244:247], v[198:201], v[32:35]
	v_mfma_f32_16x16x32_bf16 v[20:23], v[236:239], v[228:231], v[20:23]
	v_mfma_f32_16x16x32_bf16 v[16:19], v[244:247], v[228:231], v[16:19]
	s_barrier
	s_setprio 0
	s_add_u32 s60, s60, 0x30000
	s_addc_u32 s61, s61, 0
	s_mov_b32 m0, s37
	ds_read_b128 v[186:189], v168 offset:32768
	ds_read_b128 v[190:193], v168 offset:33792
	ds_read_b128 v[194:197], v168 offset:34816
	ds_read_b128 v[198:201], v168 offset:35840
	ds_read_b128 v[224:227], v168 offset:36864
	ds_read_b128 v[228:231], v168 offset:37888
	global_load_lds_dwordx4 v138, s[60:61]
	s_mov_b32 m0, s57
	s_mov_b64 exec, s[98:99]
	global_load_lds_dwordx4 v142, s[60:61]
	s_mov_b64 exec, -1
	s_setprio 1
	s_barrier
	s_waitcnt lgkmcnt(0)
	v_mfma_f32_16x16x32_bf16 v[134:137], v[154:157], v[186:189], v[134:137]
	v_mfma_f32_16x16x32_bf16 v[130:133], v[174:177], v[186:189], v[130:133]
	v_mfma_f32_16x16x32_bf16 v[92:95], v[154:157], v[194:197], v[92:95]
	v_mfma_f32_16x16x32_bf16 v[88:91], v[174:177], v[194:197], v[88:91]
	v_mfma_f32_16x16x32_bf16 v[76:79], v[154:157], v[224:227], v[76:79]
	v_mfma_f32_16x16x32_bf16 v[72:75], v[174:177], v[224:227], v[72:75]
	v_mfma_f32_16x16x32_bf16 v[134:137], v[170:173], v[190:193], v[134:137]
	v_mfma_f32_16x16x32_bf16 v[130:133], v[182:185], v[190:193], v[130:133]
	v_mfma_f32_16x16x32_bf16 v[92:95], v[170:173], v[198:201], v[92:95]
	v_mfma_f32_16x16x32_bf16 v[88:91], v[182:185], v[198:201], v[88:91]
	v_mfma_f32_16x16x32_bf16 v[76:79], v[170:173], v[228:231], v[76:79]
	v_mfma_f32_16x16x32_bf16 v[72:75], v[182:185], v[228:231], v[72:75]
	s_barrier
	s_setprio 0
	s_add_i32 s60, 0, 0x1c000
	s_add_i32 s61, s72, s18
	v_add_u32_e32 v96, s60, v163
	v_lshl_add_u64 v[160:161], v[160:161], 0, s[6:7]
	s_mov_b32 m0, s61
	ds_read_b128 v[232:235], v96
	ds_read_b128 v[236:239], v96 offset:1024
	ds_read_b128 v[240:243], v96 offset:2048
	ds_read_b128 v[244:247], v96 offset:3072
	global_load_lds_dwordx4 v[160:161], off
	v_lshl_add_u64 v[160:161], v[164:165], 0, s[6:7]
	s_add_i32 m0, s61, 0x2000
	s_nop 0
	global_load_lds_dwordx4 v[160:161], off
	s_setprio 1
	s_barrier
	s_waitcnt lgkmcnt(0)
	v_mfma_f32_16x16x32_bf16 v[110:113], v[232:235], v[186:189], v[110:113]
	v_mfma_f32_16x16x32_bf16 v[98:101], v[240:243], v[186:189], v[98:101]
	v_mfma_f32_16x16x32_bf16 v[84:87], v[232:235], v[194:197], v[84:87]
	s_mov_b32 m0, s62
	v_mfma_f32_16x16x32_bf16 v[80:83], v[240:243], v[194:197], v[80:83]
	v_lshl_add_u64 v[160:161], v[202:203], 0, s[6:7]
	v_mfma_f32_16x16x32_bf16 v[68:71], v[232:235], v[224:227], v[68:71]
	v_mfma_f32_16x16x32_bf16 v[64:67], v[240:243], v[224:227], v[64:67]
	v_mfma_f32_16x16x32_bf16 v[110:113], v[236:239], v[190:193], v[110:113]
	v_mfma_f32_16x16x32_bf16 v[98:101], v[244:247], v[190:193], v[98:101]
	v_mfma_f32_16x16x32_bf16 v[84:87], v[236:239], v[198:201], v[84:87]
	v_mfma_f32_16x16x32_bf16 v[80:83], v[244:247], v[198:201], v[80:83]
	v_mfma_f32_16x16x32_bf16 v[68:71], v[236:239], v[228:231], v[68:71]
	v_mfma_f32_16x16x32_bf16 v[64:67], v[244:247], v[228:231], v[64:67]
	s_barrier
	s_setprio 0
	ds_read_b128 v[186:189], v168 offset:49152
	ds_read_b128 v[190:193], v168 offset:50176
	ds_read_b128 v[194:197], v168 offset:51200
	ds_read_b128 v[198:201], v168 offset:52224
	ds_read_b128 v[224:227], v168 offset:53248
	ds_read_b128 v[228:231], v168 offset:54272
	global_load_lds_dwordx4 v[160:161], off
	v_lshl_add_u64 v[160:161], v[248:249], 0, s[6:7]
	s_mov_b32 m0, s63
	s_mov_b64 exec, s[98:99]
	global_load_lds_dwordx4 v[160:161], off
	s_mov_b64 exec, -1
	s_waitcnt vmcnt(10)
	s_setprio 1
	s_barrier
	s_waitcnt lgkmcnt(0)
	v_mfma_f32_16x16x32_bf16 v[60:63], v[154:157], v[186:189], v[60:63]
	v_mfma_f32_16x16x32_bf16 v[56:59], v[174:177], v[186:189], v[56:59]
	v_mfma_f32_16x16x32_bf16 v[44:47], v[154:157], v[194:197], v[44:47]
	v_mfma_f32_16x16x32_bf16 v[40:43], v[174:177], v[194:197], v[40:43]
	v_mfma_f32_16x16x32_bf16 v[28:31], v[154:157], v[224:227], v[28:31]
	v_mfma_f32_16x16x32_bf16 v[24:27], v[174:177], v[224:227], v[24:27]
	v_mfma_f32_16x16x32_bf16 v[60:63], v[170:173], v[190:193], v[60:63]
	v_mfma_f32_16x16x32_bf16 v[56:59], v[182:185], v[190:193], v[56:59]
	v_mfma_f32_16x16x32_bf16 v[44:47], v[170:173], v[198:201], v[44:47]
	v_mfma_f32_16x16x32_bf16 v[40:43], v[182:185], v[198:201], v[40:43]
	v_mfma_f32_16x16x32_bf16 v[28:31], v[170:173], v[228:231], v[28:31]
	v_mfma_f32_16x16x32_bf16 v[24:27], v[182:185], v[228:231], v[24:27]
	s_barrier
	s_setprio 0
	v_add_u32_e32 v96, 0x10000, v163
	ds_read_b128 v[154:157], v96
	ds_read_b128 v[170:173], v96 offset:1024
	ds_read_b128 v[174:177], v96 offset:2048
	ds_read_b128 v[182:185], v96 offset:3072
	s_add_u32 s58, s58, 0x40080
	s_addc_u32 s59, s59, 0
	s_add_i32 s60, s60, s18
	s_mov_b32 m0, s60
	s_nop 0
	global_load_lds_dwordx4 v140, s[58:59]
	s_add_i32 m0, s60, 0x2000
	s_nop 0
	global_load_lds_dwordx4 v144, s[58:59]
	s_waitcnt vmcnt(6)
	s_setprio 1
	s_barrier
	v_mfma_f32_16x16x32_bf16 v[52:55], v[232:235], v[186:189], v[52:55]
	v_mfma_f32_16x16x32_bf16 v[48:51], v[240:243], v[186:189], v[48:51]
	v_mfma_f32_16x16x32_bf16 v[36:39], v[232:235], v[194:197], v[36:39]
	s_add_i32 s71, s71, 2
	v_mfma_f32_16x16x32_bf16 v[32:35], v[240:243], v[194:197], v[32:35]
	s_add_u32 s42, s42, 0x100
	v_mfma_f32_16x16x32_bf16 v[20:23], v[232:235], v[224:227], v[20:23]
	s_addc_u32 s43, s43, 0
	v_mfma_f32_16x16x32_bf16 v[16:19], v[240:243], v[224:227], v[16:19]
	s_add_u32 s69, s69, 0x100
	v_mfma_f32_16x16x32_bf16 v[52:55], v[236:239], v[190:193], v[52:55]
	s_addc_u32 s70, s70, 0
	v_mfma_f32_16x16x32_bf16 v[48:51], v[244:247], v[190:193], v[48:51]
	s_cmp_gt_u32 s71, 13
	v_mfma_f32_16x16x32_bf16 v[36:39], v[236:239], v[198:201], v[36:39]
	v_mfma_f32_16x16x32_bf16 v[32:35], v[244:247], v[198:201], v[32:35]
	v_mfma_f32_16x16x32_bf16 v[20:23], v[236:239], v[228:231], v[20:23]
	v_mfma_f32_16x16x32_bf16 v[16:19], v[244:247], v[228:231], v[16:19]
	s_barrier
	s_setprio 0
	s_cbranch_scc0 .LBB0_465
	s_waitcnt lgkmcnt(0)
	s_mul_i32 s42, s67, 0xc0
	s_add_i32 s42, s42, s19
	s_cmpk_lt_u32 s42, 0x2000
	s_cselect_b32 s43, 1, 2
	v_or_b32_e32 v156, s42, v159
	v_mov_b32_e32 v96, s43
	v_cmp_lt_i32_e32 vcc, s23, v156
	v_add_u32_e32 v160, 16, v156
	v_lshl_or_b32 v154, s56, 8, v166
	v_cndmask_b32_e32 v169, 0, v96, vcc
	s_waitcnt vmcnt(0)
	v_add_f32_e32 v96, v126, v127
	v_add_f32_e32 v126, v128, v129
	v_add_f32_e32 v96, v96, v126
	v_mov_b32_e32 v126, v96
	s_nop 1
	v_permlane16_swap_b32_e32 v96, v126
	v_add_f32_e32 v96, v96, v126
	v_mov_b32_e32 v126, v96
	s_nop 1
	v_permlane32_swap_b32_e32 v96, v126
	v_add_f32_e32 v96, v96, v126
	v_fmamk_f32 v96, v96, 0x3a800000, v207
	v_rsq_f32_e32 v162, v96
	v_add_f32_e32 v96, v122, v123
	v_add_f32_e32 v122, v124, v125
	v_add_f32_e32 v96, v96, v122
	v_mov_b32_e32 v122, v96
	s_nop 1
	v_permlane16_swap_b32_e32 v96, v122
	v_add_f32_e32 v96, v96, v122
	v_mov_b32_e32 v122, v96
	s_nop 1
	v_permlane32_swap_b32_e32 v96, v122
	v_add_f32_e32 v96, v96, v122
	v_fmamk_f32 v96, v96, 0x3a800000, v207
	v_rsq_f32_e32 v158, v96
	v_add_f32_e32 v96, v118, v119
	v_add_f32_e32 v118, v120, v121
	v_add_f32_e32 v96, v96, v118
	v_mov_b32_e32 v118, v96
	s_nop 1
	v_permlane16_swap_b32_e32 v96, v118
	v_add_f32_e32 v96, v96, v118
	v_mov_b32_e32 v118, v96
	s_nop 1
	v_permlane32_swap_b32_e32 v96, v118
	v_add_f32_e32 v96, v96, v118
	v_fmamk_f32 v96, v96, 0x3a800000, v207
	v_rsq_f32_e32 v128, v96
	v_add_f32_e32 v96, v114, v115
	v_add_f32_e32 v114, v116, v117
	v_add_f32_e32 v96, v96, v114
	v_mov_b32_e32 v114, v96
	s_nop 1
	v_permlane16_swap_b32_e32 v96, v114
	v_add_f32_e32 v96, v96, v114
	v_mov_b32_e32 v114, v96
	s_nop 1
	v_permlane32_swap_b32_e32 v96, v114
	v_add_f32_e32 v96, v96, v114
	v_fmamk_f32 v96, v96, 0x3a800000, v207
	v_rsq_f32_e32 v126, v96
	v_add_f32_e32 v96, v106, v107
	v_add_f32_e32 v106, v108, v109
	v_add_f32_e32 v96, v96, v106
	v_mov_b32_e32 v106, v96
	s_nop 1
	v_permlane16_swap_b32_e32 v96, v106
	v_add_f32_e32 v96, v96, v106
	v_mov_b32_e32 v106, v96
	s_nop 1
	v_permlane32_swap_b32_e32 v96, v106
	v_add_f32_e32 v96, v96, v106
	v_fmamk_f32 v96, v96, 0x3a800000, v207
	v_rsq_f32_e32 v124, v96
	v_add_f32_e32 v96, v102, v103
	v_add_f32_e32 v102, v104, v105
	v_add_f32_e32 v96, v96, v102
	v_mov_b32_e32 v102, v96
	s_nop 1
	v_permlane16_swap_b32_e32 v96, v102
	v_add_f32_e32 v96, v96, v102
	v_mov_b32_e32 v102, v96
	s_nop 1
	v_permlane32_swap_b32_e32 v96, v102
	v_add_f32_e32 v96, v96, v102
	v_fmamk_f32 v96, v96, 0x3a800000, v207
	v_rsq_f32_e32 v122, v96
	s_mov_b64 s[58:59], -1
	s_cmp_gt_i32 s56, 3
	v_ashrrev_i32_e32 v157, 31, v156
	v_cmp_lt_i32_e32 vcc, s26, v156
	v_cmp_gt_u32_e64 s[42:43], s24, v160
	s_cbranch_scc0 .LBB0_478
	v_lshlrev_b64 v[102:103], 11, v[156:157]
	v_lshl_add_u32 v96, s56, 7, v167
	v_lshl_add_u64 v[102:103], s[48:49], 0, v[102:103]
	v_lshl_add_u64 v[106:107], v[96:97], 1, v[102:103]
	v_pk_fma_f32 v[102:103], v[136:137], v[162:163], v[6:7] op_sel_hi:[1,0,1]
	v_pk_fma_f32 v[104:105], v[134:135], v[162:163], v[4:5] op_sel_hi:[1,0,1]
	v_pk_fma_f32 v[108:109], v[112:113], v[162:163], v[14:15] op_sel_hi:[1,0,1]
	v_pk_fma_f32 v[114:115], v[110:111], v[162:163], v[12:13] op_sel_hi:[1,0,1]
	v_pk_mul_f32 v[108:109], v[102:103], v[108:109]
	v_pk_mul_f32 v[102:103], v[104:105], v[114:115]
	v_pk_fma_f32 v[104:105], v[132:133], v[162:163], v[2:3] op_sel_hi:[1,0,1]
	v_pk_fma_f32 v[114:115], v[130:131], v[162:163], v[0:1] op_sel_hi:[1,0,1]
	v_pk_fma_f32 v[116:117], v[100:101], v[162:163], v[10:11] op_sel_hi:[1,0,1]
	v_pk_fma_f32 v[118:119], v[98:99], v[162:163], v[8:9] op_sel_hi:[1,0,1]
	v_pk_mul_f32 v[116:117], v[104:105], v[116:117]
	v_pk_mul_f32 v[104:105], v[114:115], v[118:119]
	v_cvt_pk_bf16_f32 v102, v102, v103
	v_cvt_pk_bf16_f32 v103, v108, v109
	v_mov_b64_e32 v[120:121], v[14:15]
	v_cvt_pk_bf16_f32 v104, v104, v105
	v_cvt_pk_bf16_f32 v105, v116, v117
	global_store_dwordx4 v[106:107], v[102:105], off
	v_mov_b64_e32 v[116:117], v[10:11]
	v_mov_b64_e32 v[108:109], v[6:7]
	v_cndmask_b32_e64 v102, 2, 1, s[42:43]
	v_cndmask_b32_e32 v125, 0, v102, vcc
	v_mov_b64_e32 v[104:105], v[2:3]
	v_mov_b32_e32 v155, v97
	v_cmp_ne_u32_e32 vcc, v125, v169
	v_mov_b64_e32 v[114:115], v[8:9]
	v_mov_b64_e32 v[102:103], v[0:1]
	v_mov_b64_e32 v[118:119], v[12:13]
	v_mov_b64_e32 v[106:107], v[4:5]
	v_mov_b32_e32 v123, v169
	s_and_saveexec_b64 s[42:43], vcc
	s_cbranch_execz .LBB0_469
	v_mul_u32_u24_e32 v102, 0x7600, v125
	v_lshlrev_b32_e32 v102, 2, v102
	v_mov_b32_e32 v103, v97
	v_lshl_add_u64 v[102:103], s[44:45], 0, v[102:103]
	v_lshl_add_u64 v[118:119], v[154:155], 2, v[102:103]
	global_load_dwordx4 v[102:105], v[118:119], off offset:16
	global_load_dwordx4 v[106:109], v[118:119], off
	global_load_dwordx4 v[114:117], v[118:119], off offset:528
	s_nop 0
	global_load_dwordx4 v[118:121], v[118:119], off offset:512
	v_mov_b32_e32 v123, v125

.LBB0_556:
	v_mov_b64_e32 v[0:1], 0x420
	s_ashr_i32 s49, s48, 31
	v_cmp_lt_i64_e32 vcc, s[50:51], v[0:1]
	s_lshl_b64 s[50:51], s[48:49], 19
	s_add_u32 s50, s4, s50
	s_addc_u32 s51, s5, s51
	s_and_b64 s[52:53], vcc, exec
	s_cselect_b32 s49, s51, s59
	s_cselect_b32 s67, s50, s58
	s_ashr_i32 s47, s46, 31
	s_lshl_b64 s[52:53], s[46:47], 19
	s_add_u32 s52, s10, s52
	s_addc_u32 s53, s11, s53
	s_and_b64 s[62:63], vcc, exec
	s_cselect_b32 s47, s53, s61
	s_cselect_b32 s68, s52, s60
	s_add_u32 s58, s58, 0x40080
	s_addc_u32 s59, s59, 0
	s_add_u32 s69, s60, 0x100
	v_mov_b32_e32 v0, 0
	s_addc_u32 s70, s61, 0
	s_mov_b32 s71, -2
	v_mov_b32_e32 v1, v0
	v_mov_b32_e32 v2, v0
	v_mov_b32_e32 v3, v0
	v_mov_b32_e32 v4, v0
	v_mov_b32_e32 v5, v0
	v_mov_b32_e32 v6, v0
	v_mov_b32_e32 v7, v0
	v_mov_b32_e32 v16, v0
	v_mov_b32_e32 v17, v0
	v_mov_b32_e32 v18, v0
	v_mov_b32_e32 v19, v0
	v_mov_b32_e32 v20, v0
	v_mov_b32_e32 v21, v0
	v_mov_b32_e32 v22, v0
	v_mov_b32_e32 v23, v0
	v_mov_b32_e32 v32, v0
	v_mov_b32_e32 v33, v0
	v_mov_b32_e32 v34, v0
	v_mov_b32_e32 v35, v0
	v_mov_b32_e32 v36, v0
	v_mov_b32_e32 v37, v0
	v_mov_b32_e32 v38, v0
	v_mov_b32_e32 v39, v0
	v_mov_b32_e32 v48, v0
	v_mov_b32_e32 v49, v0
	v_mov_b32_e32 v50, v0
	v_mov_b32_e32 v51, v0
	v_mov_b32_e32 v52, v0
	v_mov_b32_e32 v53, v0
	v_mov_b32_e32 v54, v0
	v_mov_b32_e32 v55, v0
	v_mov_b32_e32 v8, v0
	v_mov_b32_e32 v9, v0
	v_mov_b32_e32 v10, v0
	v_mov_b32_e32 v11, v0
	v_mov_b32_e32 v12, v0
	v_mov_b32_e32 v13, v0
	v_mov_b32_e32 v14, v0
	v_mov_b32_e32 v15, v0
	v_mov_b32_e32 v24, v0
	v_mov_b32_e32 v25, v0
	v_mov_b32_e32 v26, v0
	v_mov_b32_e32 v27, v0
	v_mov_b32_e32 v28, v0
	v_mov_b32_e32 v29, v0
	v_mov_b32_e32 v30, v0
	v_mov_b32_e32 v31, v0
	v_mov_b32_e32 v40, v0
	v_mov_b32_e32 v41, v0
	v_mov_b32_e32 v42, v0
	v_mov_b32_e32 v43, v0
	v_mov_b32_e32 v44, v0
	v_mov_b32_e32 v45, v0
	v_mov_b32_e32 v46, v0
	v_mov_b32_e32 v47, v0
	v_mov_b32_e32 v56, v0
	v_mov_b32_e32 v57, v0
	v_mov_b32_e32 v58, v0
	v_mov_b32_e32 v59, v0
	v_mov_b32_e32 v60, v0
	v_mov_b32_e32 v61, v0
	v_mov_b32_e32 v62, v0
	v_mov_b32_e32 v63, v0
	v_mov_b32_e32 v64, v0
	v_mov_b32_e32 v65, v0
	v_mov_b32_e32 v66, v0
	v_mov_b32_e32 v67, v0
	v_mov_b32_e32 v68, v0
	v_mov_b32_e32 v69, v0
	v_mov_b32_e32 v70, v0
	v_mov_b32_e32 v71, v0
	v_mov_b32_e32 v84, v0
	v_mov_b32_e32 v85, v0
	v_mov_b32_e32 v86, v0
	v_mov_b32_e32 v87, v0
	v_mov_b32_e32 v92, v0
	v_mov_b32_e32 v93, v0
	v_mov_b32_e32 v94, v0
	v_mov_b32_e32 v95, v0
	v_mov_b32_e32 v114, v0
	v_mov_b32_e32 v115, v0
	v_mov_b32_e32 v116, v0
	v_mov_b32_e32 v117, v0
	v_mov_b32_e32 v118, v0
	v_mov_b32_e32 v119, v0
	v_mov_b32_e32 v120, v0
	v_mov_b32_e32 v121, v0
	v_mov_b32_e32 v130, v0
	v_mov_b32_e32 v131, v0
	v_mov_b32_e32 v132, v0
	v_mov_b32_e32 v133, v0
	v_mov_b32_e32 v134, v0
	v_mov_b32_e32 v135, v0
	v_mov_b32_e32 v136, v0
	v_mov_b32_e32 v137, v0
	v_mov_b32_e32 v72, v0
	v_mov_b32_e32 v73, v0
	v_mov_b32_e32 v74, v0
	v_mov_b32_e32 v75, v0
	v_mov_b32_e32 v76, v0
	v_mov_b32_e32 v77, v0
	v_mov_b32_e32 v78, v0
	v_mov_b32_e32 v79, v0
	v_mov_b32_e32 v98, v0
	v_mov_b32_e32 v99, v0
	v_mov_b32_e32 v100, v0
	v_mov_b32_e32 v101, v0
	v_mov_b32_e32 v110, v0
	v_mov_b32_e32 v111, v0
	v_mov_b32_e32 v112, v0
	v_mov_b32_e32 v113, v0
	v_mov_b32_e32 v122, v0
	v_mov_b32_e32 v123, v0
	v_mov_b32_e32 v124, v0
	v_mov_b32_e32 v125, v0
	v_mov_b32_e32 v126, v0
	v_mov_b32_e32 v127, v0
	v_mov_b32_e32 v128, v0
	v_mov_b32_e32 v129, v0
	v_mov_b32_e32 v138, v0
	v_mov_b32_e32 v139, v0
	v_mov_b32_e32 v140, v0
	v_mov_b32_e32 v141, v0
	v_mov_b32_e32 v142, v0
	v_mov_b32_e32 v143, v0
	v_mov_b32_e32 v144, v0
	v_mov_b32_e32 v145, v0
	v_add_u32_e32 v96, 0x10000, v193
	ds_read_b128 v[80:83], v96
	ds_read_b128 v[88:91], v96 offset:1024
	ds_read_b128 v[102:105], v96 offset:2048
	ds_read_b128 v[106:109], v96 offset:3072
.LBB0_557:
	s_add_u32 s60, s58, 0xfffc0080
	s_addc_u32 s61, s59, -1
	s_add_i32 s72, 0, 0x10000
	v_add_u32_e32 v96, s72, v193
	s_cmp_eq_u32 s71, 12
	s_cselect_b32 s63, s49, s61
	s_cselect_b32 s62, s67, s60
	s_cselect_b32 s61, s47, s70
	s_cselect_b32 s60, s68, s69
	s_add_i32 m0, s27, 0xc000
	ds_read_b128 v[160:163], v195
	ds_read_b128 v[164:167], v195 offset:1024
	ds_read_b128 v[168:171], v195 offset:2048
	ds_read_b128 v[172:175], v195 offset:3072
	ds_read_b128 v[182:185], v195 offset:4096
	ds_read_b128 v[186:189], v195 offset:5120
	ds_read_b128 v[196:199], v195 offset:6144
	ds_read_b128 v[200:203], v195 offset:7168
	global_load_lds_dwordx4 v156, s[58:59]
	s_add_i32 m0, s27, 0xe000
	s_nop 0
	global_load_lds_dwordx4 v158, s[58:59]
	s_setprio 1
	s_barrier
	s_waitcnt lgkmcnt(0)
	v_mfma_f32_16x16x32_bf16 v[142:145], v[80:83], v[160:163], v[142:145]
	v_mfma_f32_16x16x32_bf16 v[138:141], v[102:105], v[160:163], v[138:141]
	v_mfma_f32_16x16x32_bf16 v[126:129], v[80:83], v[168:171], v[126:129]
	v_mfma_f32_16x16x32_bf16 v[122:125], v[102:105], v[168:171], v[122:125]
	v_mfma_f32_16x16x32_bf16 v[110:113], v[80:83], v[182:185], v[110:113]
	v_mfma_f32_16x16x32_bf16 v[98:101], v[102:105], v[182:185], v[98:101]
	v_mfma_f32_16x16x32_bf16 v[76:79], v[80:83], v[196:199], v[76:79]
	v_mfma_f32_16x16x32_bf16 v[72:75], v[102:105], v[196:199], v[72:75]
	v_mfma_f32_16x16x32_bf16 v[142:145], v[88:91], v[164:167], v[142:145]
	v_mfma_f32_16x16x32_bf16 v[138:141], v[106:109], v[164:167], v[138:141]
	v_mfma_f32_16x16x32_bf16 v[126:129], v[88:91], v[172:175], v[126:129]
	v_mfma_f32_16x16x32_bf16 v[122:125], v[106:109], v[172:175], v[122:125]
	v_mfma_f32_16x16x32_bf16 v[110:113], v[88:91], v[186:189], v[110:113]
	v_mfma_f32_16x16x32_bf16 v[98:101], v[106:109], v[186:189], v[98:101]
	v_mfma_f32_16x16x32_bf16 v[76:79], v[88:91], v[200:203], v[76:79]
	v_mfma_f32_16x16x32_bf16 v[72:75], v[106:109], v[200:203], v[72:75]
	s_barrier
	s_setprio 0
	s_add_i32 s76, 0, 0x14000
	s_add_i32 s72, s72, s18
	v_add_u32_e32 v96, s76, v193
	v_lshl_add_u64 v[176:177], s[60:61], 0, v[150:151]
	s_mov_b32 m0, s72
	ds_read_b128 v[224:227], v96
	ds_read_b128 v[228:231], v96 offset:1024
	ds_read_b128 v[232:235], v96 offset:2048
	ds_read_b128 v[236:239], v96 offset:3072
	global_load_lds_dwordx4 v150, s[60:61]
	v_lshl_add_u64 v[190:191], s[60:61], 0, v[146:147]
	s_add_i32 m0, s72, 0x2000
	s_nop 0
	global_load_lds_dwordx4 v146, s[60:61]
	s_setprio 1
	s_barrier
	s_waitcnt lgkmcnt(0)
	v_mfma_f32_16x16x32_bf16 v[134:137], v[224:227], v[160:163], v[134:137]
	v_mfma_f32_16x16x32_bf16 v[130:133], v[232:235], v[160:163], v[130:133]
	v_mfma_f32_16x16x32_bf16 v[118:121], v[224:227], v[168:171], v[118:121]
	s_mov_b32 m0, s27
	v_mfma_f32_16x16x32_bf16 v[114:117], v[232:235], v[168:171], v[114:117]
	v_lshl_add_u64 v[240:241], s[62:63], 0, v[152:153]
	v_mfma_f32_16x16x32_bf16 v[92:95], v[224:227], v[182:185], v[92:95]
	v_mfma_f32_16x16x32_bf16 v[84:87], v[232:235], v[182:185], v[84:87]
	v_mfma_f32_16x16x32_bf16 v[68:71], v[224:227], v[196:199], v[68:71]
	v_mfma_f32_16x16x32_bf16 v[64:67], v[232:235], v[196:199], v[64:67]
	v_mfma_f32_16x16x32_bf16 v[134:137], v[228:231], v[164:167], v[134:137]
	v_mfma_f32_16x16x32_bf16 v[130:133], v[236:239], v[164:167], v[130:133]
	v_mfma_f32_16x16x32_bf16 v[118:121], v[228:231], v[172:175], v[118:121]
	v_mfma_f32_16x16x32_bf16 v[114:117], v[236:239], v[172:175], v[114:117]
	v_mfma_f32_16x16x32_bf16 v[92:95], v[228:231], v[186:189], v[92:95]
	v_mfma_f32_16x16x32_bf16 v[84:87], v[236:239], v[186:189], v[84:87]
	v_mfma_f32_16x16x32_bf16 v[68:71], v[228:231], v[200:203], v[68:71]
	v_mfma_f32_16x16x32_bf16 v[64:67], v[236:239], v[200:203], v[64:67]
	s_barrier
	s_setprio 0
	ds_read_b128 v[160:163], v195 offset:16384
	ds_read_b128 v[164:167], v195 offset:17408
	ds_read_b128 v[168:171], v195 offset:18432
	ds_read_b128 v[172:175], v195 offset:19456
	ds_read_b128 v[182:185], v195 offset:20480
	ds_read_b128 v[186:189], v195 offset:21504
	ds_read_b128 v[196:199], v195 offset:22528
	ds_read_b128 v[200:203], v195 offset:23552
	global_load_lds_dwordx4 v152, s[62:63]
	v_lshl_add_u64 v[242:243], s[62:63], 0, v[148:149]
	s_mov_b32 m0, s28
	s_nop 0
	global_load_lds_dwordx4 v148, s[62:63]
	s_waitcnt vmcnt(10)
	s_setprio 1
	s_barrier
	s_waitcnt lgkmcnt(0)
	v_mfma_f32_16x16x32_bf16 v[60:63], v[80:83], v[160:163], v[60:63]
	v_mfma_f32_16x16x32_bf16 v[56:59], v[102:105], v[160:163], v[56:59]
	v_mfma_f32_16x16x32_bf16 v[44:47], v[80:83], v[168:171], v[44:47]
	v_mfma_f32_16x16x32_bf16 v[40:43], v[102:105], v[168:171], v[40:43]
	v_mfma_f32_16x16x32_bf16 v[28:31], v[80:83], v[182:185], v[28:31]
	v_mfma_f32_16x16x32_bf16 v[24:27], v[102:105], v[182:185], v[24:27]
	v_mfma_f32_16x16x32_bf16 v[12:15], v[80:83], v[196:199], v[12:15]
	v_mfma_f32_16x16x32_bf16 v[8:11], v[102:105], v[196:199], v[8:11]
	v_mfma_f32_16x16x32_bf16 v[60:63], v[88:91], v[164:167], v[60:63]
	v_mfma_f32_16x16x32_bf16 v[56:59], v[106:109], v[164:167], v[56:59]
	v_mfma_f32_16x16x32_bf16 v[44:47], v[88:91], v[172:175], v[44:47]
	v_mfma_f32_16x16x32_bf16 v[40:43], v[106:109], v[172:175], v[40:43]
	v_mfma_f32_16x16x32_bf16 v[28:31], v[88:91], v[186:189], v[28:31]
	v_mfma_f32_16x16x32_bf16 v[24:27], v[106:109], v[186:189], v[24:27]
	v_mfma_f32_16x16x32_bf16 v[12:15], v[88:91], v[200:203], v[12:15]
	v_mfma_f32_16x16x32_bf16 v[8:11], v[106:109], v[200:203], v[8:11]
	s_barrier
	s_setprio 0
	v_add_u32_e32 v96, 0x18000, v193
	ds_read_b128 v[80:83], v96
	ds_read_b128 v[88:91], v96 offset:1024
	ds_read_b128 v[102:105], v96 offset:2048
	ds_read_b128 v[106:109], v96 offset:3072
	s_add_u32 s74, s60, 0x40000
	s_addc_u32 s75, s61, 0
	s_add_i32 s72, s76, s18
	s_mov_b32 m0, s72
	s_nop 0
	global_load_lds_dwordx4 v150, s[74:75]
	s_add_i32 m0, s72, 0x2000
	s_nop 0
	global_load_lds_dwordx4 v146, s[74:75]
	s_waitcnt vmcnt(6)
	s_setprio 1
	s_barrier
	v_mfma_f32_16x16x32_bf16 v[52:55], v[224:227], v[160:163], v[52:55]
	v_mfma_f32_16x16x32_bf16 v[48:51], v[232:235], v[160:163], v[48:51]
	v_mfma_f32_16x16x32_bf16 v[36:39], v[224:227], v[168:171], v[36:39]
	s_add_i32 s72, 0, 0x18000
	v_mfma_f32_16x16x32_bf16 v[32:35], v[232:235], v[168:171], v[32:35]
	v_add_u32_e32 v96, s72, v193
	v_mfma_f32_16x16x32_bf16 v[20:23], v[224:227], v[182:185], v[20:23]
	v_mfma_f32_16x16x32_bf16 v[16:19], v[232:235], v[182:185], v[16:19]
	v_mfma_f32_16x16x32_bf16 v[4:7], v[224:227], v[196:199], v[4:7]
	v_mfma_f32_16x16x32_bf16 v[0:3], v[232:235], v[196:199], v[0:3]
	v_mfma_f32_16x16x32_bf16 v[52:55], v[228:231], v[164:167], v[52:55]
	v_mfma_f32_16x16x32_bf16 v[48:51], v[236:239], v[164:167], v[48:51]
	v_mfma_f32_16x16x32_bf16 v[36:39], v[228:231], v[172:175], v[36:39]
	v_mfma_f32_16x16x32_bf16 v[32:35], v[236:239], v[172:175], v[32:35]
	v_mfma_f32_16x16x32_bf16 v[20:23], v[228:231], v[186:189], v[20:23]
	v_mfma_f32_16x16x32_bf16 v[16:19], v[236:239], v[186:189], v[16:19]
	v_mfma_f32_16x16x32_bf16 v[4:7], v[228:231], v[200:203], v[4:7]
	v_mfma_f32_16x16x32_bf16 v[0:3], v[236:239], v[200:203], v[0:3]
	s_barrier
	s_setprio 0
	s_add_u32 s62, s62, 0x40000
	s_addc_u32 s63, s63, 0
	s_mov_b32 m0, s37
	ds_read_b128 v[160:163], v195 offset:32768
	ds_read_b128 v[164:167], v195 offset:33792
	ds_read_b128 v[168:171], v195 offset:34816
	ds_read_b128 v[172:175], v195 offset:35840
	ds_read_b128 v[182:185], v195 offset:36864
	ds_read_b128 v[186:189], v195 offset:37888
	ds_read_b128 v[196:199], v195 offset:38912
	ds_read_b128 v[200:203], v195 offset:39936
	global_load_lds_dwordx4 v152, s[62:63]
	s_mov_b32 m0, s56
	s_nop 0
	global_load_lds_dwordx4 v148, s[62:63]
	s_setprio 1
	s_barrier
	s_waitcnt lgkmcnt(0)
	v_mfma_f32_16x16x32_bf16 v[142:145], v[80:83], v[160:163], v[142:145]
	v_mfma_f32_16x16x32_bf16 v[138:141], v[102:105], v[160:163], v[138:141]
	v_mfma_f32_16x16x32_bf16 v[126:129], v[80:83], v[168:171], v[126:129]
	v_mfma_f32_16x16x32_bf16 v[122:125], v[102:105], v[168:171], v[122:125]
	v_mfma_f32_16x16x32_bf16 v[110:113], v[80:83], v[182:185], v[110:113]
	v_mfma_f32_16x16x32_bf16 v[98:101], v[102:105], v[182:185], v[98:101]
	v_mfma_f32_16x16x32_bf16 v[76:79], v[80:83], v[196:199], v[76:79]
	v_mfma_f32_16x16x32_bf16 v[72:75], v[102:105], v[196:199], v[72:75]
	v_mfma_f32_16x16x32_bf16 v[142:145], v[88:91], v[164:167], v[142:145]
	v_mfma_f32_16x16x32_bf16 v[138:141], v[106:109], v[164:167], v[138:141]
	v_mfma_f32_16x16x32_bf16 v[126:129], v[88:91], v[172:175], v[126:129]
	v_mfma_f32_16x16x32_bf16 v[122:125], v[106:109], v[172:175], v[122:125]
	v_mfma_f32_16x16x32_bf16 v[110:113], v[88:91], v[186:189], v[110:113]
	v_mfma_f32_16x16x32_bf16 v[98:101], v[106:109], v[186:189], v[98:101]
	v_mfma_f32_16x16x32_bf16 v[76:79], v[88:91], v[200:203], v[76:79]
	v_mfma_f32_16x16x32_bf16 v[72:75], v[106:109], v[200:203], v[72:75]
	s_barrier
	s_setprio 0
	s_add_i32 s62, 0, 0x1c000
	s_add_i32 s63, s72, s18
	v_add_u32_e32 v96, s62, v193
	v_lshl_add_u64 v[176:177], v[176:177], 0, s[6:7]
	s_mov_b32 m0, s63
	ds_read_b128 v[224:227], v96
	ds_read_b128 v[228:231], v96 offset:1024
	ds_read_b128 v[232:235], v96 offset:2048
	ds_read_b128 v[236:239], v96 offset:3072
	global_load_lds_dwordx4 v[176:177], off
	v_lshl_add_u64 v[176:177], v[190:191], 0, s[6:7]
	s_add_i32 m0, s63, 0x2000
	s_nop 0
	global_load_lds_dwordx4 v[176:177], off
	s_setprio 1
	s_barrier
	s_waitcnt lgkmcnt(0)
	v_mfma_f32_16x16x32_bf16 v[134:137], v[224:227], v[160:163], v[134:137]
	v_mfma_f32_16x16x32_bf16 v[130:133], v[232:235], v[160:163], v[130:133]
	v_mfma_f32_16x16x32_bf16 v[118:121], v[224:227], v[168:171], v[118:121]
	s_mov_b32 m0, s64
	v_mfma_f32_16x16x32_bf16 v[114:117], v[232:235], v[168:171], v[114:117]
	v_lshl_add_u64 v[176:177], v[240:241], 0, s[6:7]
	v_mfma_f32_16x16x32_bf16 v[92:95], v[224:227], v[182:185], v[92:95]
	v_mfma_f32_16x16x32_bf16 v[84:87], v[232:235], v[182:185], v[84:87]
	v_mfma_f32_16x16x32_bf16 v[68:71], v[224:227], v[196:199], v[68:71]
	v_mfma_f32_16x16x32_bf16 v[64:67], v[232:235], v[196:199], v[64:67]
	v_mfma_f32_16x16x32_bf16 v[134:137], v[228:231], v[164:167], v[134:137]
	v_mfma_f32_16x16x32_bf16 v[130:133], v[236:239], v[164:167], v[130:133]
	v_mfma_f32_16x16x32_bf16 v[118:121], v[228:231], v[172:175], v[118:121]
	v_mfma_f32_16x16x32_bf16 v[114:117], v[236:239], v[172:175], v[114:117]
	v_mfma_f32_16x16x32_bf16 v[92:95], v[228:231], v[186:189], v[92:95]
	v_mfma_f32_16x16x32_bf16 v[84:87], v[236:239], v[186:189], v[84:87]
	v_mfma_f32_16x16x32_bf16 v[68:71], v[228:231], v[200:203], v[68:71]
	v_mfma_f32_16x16x32_bf16 v[64:67], v[236:239], v[200:203], v[64:67]
	s_barrier
	s_setprio 0
	ds_read_b128 v[160:163], v195 offset:49152
	ds_read_b128 v[164:167], v195 offset:50176
	ds_read_b128 v[168:171], v195 offset:51200
	ds_read_b128 v[172:175], v195 offset:52224
	ds_read_b128 v[182:185], v195 offset:53248
	ds_read_b128 v[186:189], v195 offset:54272
	ds_read_b128 v[196:199], v195 offset:55296
	ds_read_b128 v[200:203], v195 offset:56320
	global_load_lds_dwordx4 v[176:177], off
	v_lshl_add_u64 v[176:177], v[242:243], 0, s[6:7]
	s_mov_b32 m0, s65
	s_nop 0
	global_load_lds_dwordx4 v[176:177], off
	s_waitcnt vmcnt(10)
	s_setprio 1
	s_barrier
	s_waitcnt lgkmcnt(0)
	v_mfma_f32_16x16x32_bf16 v[60:63], v[80:83], v[160:163], v[60:63]
	v_mfma_f32_16x16x32_bf16 v[56:59], v[102:105], v[160:163], v[56:59]
	v_mfma_f32_16x16x32_bf16 v[44:47], v[80:83], v[168:171], v[44:47]
	v_mfma_f32_16x16x32_bf16 v[40:43], v[102:105], v[168:171], v[40:43]
	v_mfma_f32_16x16x32_bf16 v[28:31], v[80:83], v[182:185], v[28:31]
	v_mfma_f32_16x16x32_bf16 v[24:27], v[102:105], v[182:185], v[24:27]
	v_mfma_f32_16x16x32_bf16 v[12:15], v[80:83], v[196:199], v[12:15]
	v_mfma_f32_16x16x32_bf16 v[8:11], v[102:105], v[196:199], v[8:11]
	v_mfma_f32_16x16x32_bf16 v[60:63], v[88:91], v[164:167], v[60:63]
	v_mfma_f32_16x16x32_bf16 v[56:59], v[106:109], v[164:167], v[56:59]
	v_mfma_f32_16x16x32_bf16 v[44:47], v[88:91], v[172:175], v[44:47]
	v_mfma_f32_16x16x32_bf16 v[40:43], v[106:109], v[172:175], v[40:43]
	v_mfma_f32_16x16x32_bf16 v[28:31], v[88:91], v[186:189], v[28:31]
	v_mfma_f32_16x16x32_bf16 v[24:27], v[106:109], v[186:189], v[24:27]
	v_mfma_f32_16x16x32_bf16 v[12:15], v[88:91], v[200:203], v[12:15]
	v_mfma_f32_16x16x32_bf16 v[8:11], v[106:109], v[200:203], v[8:11]
	s_barrier
	s_setprio 0
	v_add_u32_e32 v96, 0x10000, v193
	ds_read_b128 v[80:83], v96
	ds_read_b128 v[88:91], v96 offset:1024
	ds_read_b128 v[102:105], v96 offset:2048
	ds_read_b128 v[106:109], v96 offset:3072
	s_add_u32 s60, s60, 0x40080
	s_addc_u32 s61, s61, 0
	s_add_i32 s62, s62, s18
	s_mov_b32 m0, s62
	s_nop 0
	global_load_lds_dwordx4 v150, s[60:61]
	s_add_i32 m0, s62, 0x2000
	s_nop 0
	global_load_lds_dwordx4 v146, s[60:61]
	s_waitcnt vmcnt(6)
	s_setprio 1
	s_barrier
	v_mfma_f32_16x16x32_bf16 v[52:55], v[224:227], v[160:163], v[52:55]
	v_mfma_f32_16x16x32_bf16 v[48:51], v[232:235], v[160:163], v[48:51]
	v_mfma_f32_16x16x32_bf16 v[36:39], v[224:227], v[168:171], v[36:39]
	s_add_i32 s71, s71, 2
	v_mfma_f32_16x16x32_bf16 v[32:35], v[232:235], v[168:171], v[32:35]
	s_add_u32 s58, s58, 0x100
	v_mfma_f32_16x16x32_bf16 v[20:23], v[224:227], v[182:185], v[20:23]
	s_addc_u32 s59, s59, 0
	v_mfma_f32_16x16x32_bf16 v[16:19], v[232:235], v[182:185], v[16:19]
	s_add_u32 s69, s69, 0x100
	v_mfma_f32_16x16x32_bf16 v[4:7], v[224:227], v[196:199], v[4:7]
	s_addc_u32 s70, s70, 0
	v_mfma_f32_16x16x32_bf16 v[0:3], v[232:235], v[196:199], v[0:3]
	s_cmp_gt_u32 s71, 13
	v_mfma_f32_16x16x32_bf16 v[52:55], v[228:231], v[164:167], v[52:55]
	v_mfma_f32_16x16x32_bf16 v[48:51], v[236:239], v[164:167], v[48:51]
	v_mfma_f32_16x16x32_bf16 v[36:39], v[228:231], v[172:175], v[36:39]
	v_mfma_f32_16x16x32_bf16 v[32:35], v[236:239], v[172:175], v[32:35]
	v_mfma_f32_16x16x32_bf16 v[20:23], v[228:231], v[186:189], v[20:23]
	v_mfma_f32_16x16x32_bf16 v[16:19], v[236:239], v[186:189], v[16:19]
	v_mfma_f32_16x16x32_bf16 v[4:7], v[228:231], v[200:203], v[4:7]
	v_mfma_f32_16x16x32_bf16 v[0:3], v[236:239], v[200:203], v[0:3]
	s_barrier
	s_setprio 0
	s_cbranch_scc0 .LBB0_557
	s_waitcnt lgkmcnt(0)
	s_lshl_b32 s47, s54, 8
	s_add_i32 s47, s47, s57
	v_or_b32_e32 v162, s47, v192
	v_ashrrev_i32_e32 v163, 31, v162
	v_or_b32_e32 v190, 16, v162
	v_lshlrev_b64 v[80:81], 6, v[162:163]
	v_ashrrev_i32_e32 v191, 31, v190
	v_or_b32_e32 v188, 32, v162
	v_lshl_add_u64 v[80:81], v[154:155], 0, v[80:81]
	v_lshlrev_b64 v[82:83], 6, v[190:191]
	v_ashrrev_i32_e32 v189, 31, v188
	v_lshl_add_u64 v[82:83], v[154:155], 0, v[82:83]
	global_load_dwordx4 v[174:177], v[80:81], off
	global_load_dwordx4 v[196:199], v[82:83], off
	v_lshlrev_b64 v[80:81], 6, v[188:189]
	v_or_b32_e32 v186, 48, v162
	v_lshl_add_u64 v[80:81], v[154:155], 0, v[80:81]
	v_ashrrev_i32_e32 v187, 31, v186
	global_load_dwordx4 v[200:203], v[80:81], off
	v_lshlrev_b64 v[80:81], 6, v[186:187]
	v_lshl_add_u64 v[80:81], v[154:155], 0, v[80:81]
	v_add_u32_e32 v184, 0x80, v162
	global_load_dwordx4 v[224:227], v[80:81], off
	v_ashrrev_i32_e32 v185, 31, v184
	v_lshlrev_b64 v[80:81], 6, v[184:185]
	v_lshl_add_u64 v[80:81], v[154:155], 0, v[80:81]
	global_load_dwordx4 v[228:231], v[80:81], off
	v_add_u32_e32 v172, 0x90, v162
	v_ashrrev_i32_e32 v173, 31, v172
	v_lshlrev_b64 v[80:81], 6, v[172:173]
	v_lshl_add_u64 v[80:81], v[154:155], 0, v[80:81]
	global_load_dwordx4 v[232:235], v[80:81], off
	v_add_u32_e32 v168, 0xa0, v162
	v_ashrrev_i32_e32 v169, 31, v168
	v_lshlrev_b64 v[80:81], 6, v[168:169]
	v_lshl_add_u64 v[80:81], v[154:155], 0, v[80:81]
	global_load_dwordx4 v[236:239], v[80:81], off
	v_add_u32_e32 v164, 0xb0, v162
	v_ashrrev_i32_e32 v165, 31, v164
	v_lshlrev_b64 v[80:81], 6, v[164:165]
	s_cmpk_lt_u32 s47, 0x2000
	v_lshl_add_u64 v[80:81], v[154:155], 0, v[80:81]
	s_cselect_b32 s47, 1, 2
	global_load_dwordx4 v[240:243], v[80:81], off
	v_mov_b32_e32 v218, s47
	v_cmp_lt_i32_e32 vcc, s23, v162
	v_lshl_or_b32 v166, s55, 8, v194
	v_ashrrev_i32_e32 v167, 31, v166
	v_cndmask_b32_e32 v185, 0, v218, vcc
	v_mul_u32_u24_e32 v82, 0x7600, v185
	v_lshlrev_b32_e32 v96, 2, v82
	v_lshl_add_u64 v[80:81], s[44:45], 0, v[96:97]
	v_lshl_add_u64 v[106:107], v[166:167], 2, v[80:81]
	global_load_dwordx4 v[80:83], v[106:107], off offset:16
	global_load_dwordx4 v[88:91], v[106:107], off
	global_load_dwordx4 v[102:105], v[106:107], off offset:528
	s_nop 0
	global_load_dwordx4 v[106:109], v[106:107], off offset:512
	v_lshl_or_b32 v160, s55, 7, v194
	v_cmp_lt_i32_e32 vcc, s23, v190
	s_waitcnt vmcnt(0)
	v_add_f32_e32 v96, v174, v175
	v_add_f32_e32 v161, v176, v177
	v_add_f32_e32 v96, v96, v161
	v_add_f32_e32 v161, v196, v197
	v_add_f32_e32 v163, v198, v199
	v_add_f32_e32 v161, v161, v163
	v_add_f32_e32 v165, v200, v201
	v_add_f32_e32 v169, v202, v203
	v_add_f32_e32 v163, v165, v169
	v_mov_b32_e32 v169, v161
	v_add_f32_e32 v170, v224, v225
	v_add_f32_e32 v171, v226, v227
	v_add_f32_e32 v165, v170, v171
	v_mov_b32_e32 v170, v163
	v_permlane16_swap_b32_e32 v161, v169
	s_nop 0
	v_permlane16_swap_b32_e32 v163, v170
	v_add_f32_e32 v201, v161, v169
	v_add_f32_e32 v199, v163, v170
	v_add_f32_e32 v161, v228, v229
	v_add_f32_e32 v163, v230, v231
	v_add_f32_e32 v161, v161, v163
	v_mov_b32_e32 v163, v161
	s_nop 1
	v_permlane16_swap_b32_e32 v161, v163
	v_add_f32_e32 v191, v161, v163
	v_add_f32_e32 v161, v232, v233
	v_add_f32_e32 v163, v234, v235
	v_add_f32_e32 v161, v161, v163
	v_mov_b32_e32 v173, v96
	v_mov_b32_e32 v163, v161
	s_nop 0
	v_permlane16_swap_b32_e32 v96, v173
	v_permlane16_swap_b32_e32 v161, v163
	v_add_f32_e32 v96, v96, v173
	v_add_f32_e32 v187, v161, v163
	v_add_f32_e32 v161, v236, v237
	v_add_f32_e32 v163, v238, v239
	v_mov_b32_e32 v173, v96
	v_add_f32_e32 v161, v161, v163
	s_nop 0
	v_permlane32_swap_b32_e32 v96, v173
	v_mov_b32_e32 v163, v161
	v_add_f32_e32 v96, v96, v173
	s_nop 0
	v_permlane16_swap_b32_e32 v161, v163
	v_fmamk_f32 v96, v96, 0x3a800000, v207
	v_add_f32_e32 v169, v161, v163
	v_add_f32_e32 v161, v240, v241
	v_add_f32_e32 v163, v242, v243
	v_mov_b32_e32 v171, v165
	v_rsq_f32_e32 v96, v96
	v_add_f32_e32 v161, v161, v163
	v_permlane16_swap_b32_e32 v165, v171
	v_mov_b32_e32 v163, v161
	v_add_f32_e32 v197, v165, v171
	s_nop 0
	v_permlane16_swap_b32_e32 v161, v163
	v_mov_b64_e32 v[170:171], s[42:43]
	v_add_f32_e32 v163, v161, v163
	v_ashrrev_i32_e32 v161, 31, v160
	v_mad_i64_i32 v[170:171], s[54:55], v162, s31, v[170:171]
	v_lshl_add_u64 v[224:225], v[160:161], 1, v[170:171]
	v_pk_mul_f32 v[182:183], v[82:83], s[0:1] op_sel_hi:[1,0]
	v_pk_mul_f32 v[176:177], v[80:81], s[0:1] op_sel_hi:[1,0]
	v_pk_mul_f32 v[174:175], v[90:91], s[0:1] op_sel_hi:[1,0]
	v_pk_mul_f32 v[170:171], v[88:89], s[0:1] op_sel_hi:[1,0]
	v_mul_f32_e32 v226, 0xbfb8aa3b, v96
	v_pk_fma_f32 v[228:229], v[144:145], v[226:227], v[174:175] op_sel_hi:[1,0,1]
	v_pk_fma_f32 v[230:231], v[142:143], v[226:227], v[170:171] op_sel_hi:[1,0,1]
	v_pk_fma_f32 v[232:233], v[140:141], v[226:227], v[182:183] op_sel_hi:[1,0,1]
	v_pk_fma_f32 v[226:227], v[138:139], v[226:227], v[176:177] op_sel_hi:[1,0,1]
	v_exp_f32_e32 v230, v230
	v_exp_f32_e32 v226, v226
	v_exp_f32_e32 v231, v231
	v_exp_f32_e32 v227, v227
	v_exp_f32_e32 v232, v232
	v_exp_f32_e32 v233, v233
	v_exp_f32_e32 v228, v228
	v_exp_f32_e32 v229, v229
	v_pk_add_f32 v[230:231], v[230:231], 1.0 op_sel_hi:[1,0]
	v_pk_add_f32 v[232:233], v[232:233], 1.0 op_sel_hi:[1,0]
	v_pk_add_f32 v[226:227], v[226:227], 1.0 op_sel_hi:[1,0]
	v_pk_add_f32 v[228:229], v[228:229], 1.0 op_sel_hi:[1,0]
	v_rcp_f32_e32 v230, v230
	v_rcp_f32_e32 v226, v226
	v_rcp_f32_e32 v231, v231
	v_rcp_f32_e32 v227, v227
	v_rcp_f32_e32 v232, v232
	v_rcp_f32_e32 v233, v233
	v_rcp_f32_e32 v228, v228
	v_rcp_f32_e32 v229, v229
	v_pk_fma_f32 v[142:143], v[142:143], v[96:97], v[88:89] op_sel_hi:[1,0,1]
	v_pk_fma_f32 v[140:141], v[140:141], v[96:97], v[82:83] op_sel_hi:[1,0,1]
	v_pk_fma_f32 v[138:139], v[138:139], v[96:97], v[80:81] op_sel_hi:[1,0,1]
	v_pk_fma_f32 v[134:135], v[134:135], v[96:97], v[106:107] op_sel_hi:[1,0,1]
	v_pk_fma_f32 v[132:133], v[132:133], v[96:97], v[104:105] op_sel_hi:[1,0,1]
	v_pk_fma_f32 v[130:131], v[130:131], v[96:97], v[102:103] op_sel_hi:[1,0,1]
	v_pk_fma_f32 v[144:145], v[144:145], v[96:97], v[90:91] op_sel_hi:[1,0,1]
	v_pk_fma_f32 v[136:137], v[136:137], v[96:97], v[108:109] op_sel_hi:[1,0,1]
	v_pk_mul_f32 v[134:135], v[142:143], v[134:135]
	v_pk_mul_f32 v[132:133], v[140:141], v[132:133]
	v_pk_mul_f32 v[130:131], v[138:139], v[130:131]
	v_pk_mul_f32 v[136:137], v[144:145], v[136:137]
	v_pk_mul_f32 v[134:135], v[134:135], v[230:231]
	v_pk_mul_f32 v[138:139], v[132:133], v[232:233]
	v_pk_mul_f32 v[132:133], v[130:131], v[226:227]
	v_cvt_pk_bf16_f32 v130, v134, v135
	v_mov_b32_e32 v202, v201
	v_mov_b32_e32 v200, v199
	v_mov_b32_e32 v198, v197
	v_mov_b32_e32 v196, v191
	v_mov_b32_e32 v189, v187
	v_mov_b32_e32 v173, v169
	v_mov_b32_e32 v165, v163
	v_pk_mul_f32 v[136:137], v[136:137], v[228:229]
	v_permlane32_swap_b32_e32 v201, v202
	v_cvt_pk_bf16_f32 v131, v136, v137
	v_cvt_pk_bf16_f32 v132, v132, v133
	v_cvt_pk_bf16_f32 v133, v138, v139
	global_store_dwordx4 v[224:225], v[130:133], off
	v_permlane32_swap_b32_e32 v199, v200
	s_nop 0
	v_cndmask_b32_e32 v130, 0, v218, vcc
	v_permlane32_swap_b32_e32 v197, v198
	v_permlane32_swap_b32_e32 v191, v196
	v_permlane32_swap_b32_e32 v187, v189
	v_permlane32_swap_b32_e32 v169, v173
	v_permlane32_swap_b32_e32 v163, v165
	v_cmp_ne_u32_e32 vcc, v130, v185
	s_and_saveexec_b64 s[54:55], vcc
	s_cbranch_execz .LBB0_560
	v_mul_u32_u24_e32 v80, 0x7600, v130
	v_lshlrev_b32_e32 v96, 2, v80
	v_lshl_add_u64 v[80:81], s[44:45], 0, v[96:97]
	v_lshl_add_u64 v[106:107], v[166:167], 2, v[80:81]
	global_load_dwordx4 v[88:91], v[106:107], off
	global_load_dwordx4 v[80:83], v[106:107], off offset:16
	global_load_dwordx4 v[102:105], v[106:107], off offset:528
	s_nop 0
	global_load_dwordx4 v[106:109], v[106:107], off offset:512
	v_mov_b32_e32 v185, v130
	s_waitcnt vmcnt(0)
	v_pk_mul_f32 v[170:171], v[88:89], s[0:1] op_sel_hi:[1,0]
	v_pk_mul_f32 v[174:175], v[90:91], s[0:1] op_sel_hi:[1,0]
	v_pk_mul_f32 v[176:177], v[80:81], s[0:1] op_sel_hi:[1,0]
	v_pk_mul_f32 v[182:183], v[82:83], s[0:1] op_sel_hi:[1,0]

.LBB0_1020:
	s_add_u32 s44, s84, 0x80
	s_addc_u32 s45, s85, 0
	s_add_u32 s87, s46, 0x100
	v_mov_b32_e32 v16, 0
	s_addc_u32 vcc_lo, s47, 0
	s_mov_b32 s46, 0
	v_mov_b32_e32 v17, v16
	v_mov_b32_e32 v18, v16
	v_mov_b32_e32 v19, v16
	v_mov_b32_e32 v20, v16
	v_mov_b32_e32 v21, v16
	v_mov_b32_e32 v22, v16
	v_mov_b32_e32 v23, v16
	v_mov_b32_e32 v40, v16
	v_mov_b32_e32 v41, v16
	v_mov_b32_e32 v42, v16
	v_mov_b32_e32 v43, v16
	v_mov_b32_e32 v44, v16
	v_mov_b32_e32 v45, v16
	v_mov_b32_e32 v46, v16
	v_mov_b32_e32 v47, v16
	v_mov_b32_e32 v72, v16
	v_mov_b32_e32 v73, v16
	v_mov_b32_e32 v74, v16
	v_mov_b32_e32 v75, v16
	v_mov_b32_e32 v76, v16
	v_mov_b32_e32 v77, v16
	v_mov_b32_e32 v78, v16
	v_mov_b32_e32 v79, v16
	v_mov_b32_e32 v24, v16
	v_mov_b32_e32 v25, v16
	v_mov_b32_e32 v26, v16
	v_mov_b32_e32 v27, v16
	v_mov_b32_e32 v28, v16
	v_mov_b32_e32 v29, v16
	v_mov_b32_e32 v30, v16
	v_mov_b32_e32 v31, v16
	v_mov_b32_e32 v48, v16
	v_mov_b32_e32 v49, v16
	v_mov_b32_e32 v50, v16
	v_mov_b32_e32 v51, v16
	v_mov_b32_e32 v52, v16
	v_mov_b32_e32 v53, v16
	v_mov_b32_e32 v54, v16
	v_mov_b32_e32 v55, v16
	v_mov_b32_e32 v84, v16
	v_mov_b32_e32 v85, v16
	v_mov_b32_e32 v86, v16
	v_mov_b32_e32 v87, v16
	v_mov_b32_e32 v88, v16
	v_mov_b32_e32 v89, v16
	v_mov_b32_e32 v90, v16
	v_mov_b32_e32 v91, v16
	v_mov_b32_e32 v116, v16
	v_mov_b32_e32 v117, v16
	v_mov_b32_e32 v118, v16
	v_mov_b32_e32 v119, v16
	v_mov_b32_e32 v120, v16
	v_mov_b32_e32 v121, v16
	v_mov_b32_e32 v122, v16
	v_mov_b32_e32 v123, v16
	v_mov_b32_e32 v144, v16
	v_mov_b32_e32 v145, v16
	v_mov_b32_e32 v146, v16
	v_mov_b32_e32 v147, v16
	v_mov_b32_e32 v148, v16
	v_mov_b32_e32 v149, v16
	v_mov_b32_e32 v150, v16
	v_mov_b32_e32 v151, v16
	v_mov_b32_e32 v160, v16
	v_mov_b32_e32 v161, v16
	v_mov_b32_e32 v162, v16
	v_mov_b32_e32 v163, v16
	v_mov_b32_e32 v164, v16
	v_mov_b32_e32 v165, v16
	v_mov_b32_e32 v166, v16
	v_mov_b32_e32 v167, v16
	v_mov_b32_e32 v128, v16
	v_mov_b32_e32 v129, v16
	v_mov_b32_e32 v130, v16
	v_mov_b32_e32 v131, v16
	v_mov_b32_e32 v132, v16
	v_mov_b32_e32 v133, v16
	v_mov_b32_e32 v134, v16
	v_mov_b32_e32 v135, v16
	v_mov_b32_e32 v152, v16
	v_mov_b32_e32 v153, v16
	v_mov_b32_e32 v154, v16
	v_mov_b32_e32 v155, v16
	v_mov_b32_e32 v156, v16
	v_mov_b32_e32 v157, v16
	v_mov_b32_e32 v158, v16
	v_mov_b32_e32 v159, v16
	v_mov_b32_e32 v168, v16
	v_mov_b32_e32 v169, v16
	v_mov_b32_e32 v170, v16
	v_mov_b32_e32 v171, v16
	v_mov_b32_e32 v172, v16
	v_mov_b32_e32 v173, v16
	v_mov_b32_e32 v174, v16
	v_mov_b32_e32 v175, v16
	s_waitcnt vmcnt(0)
	v_add_u32_e32 v96, 0x10000, v225
	ds_read_b128 v[80:83], v96 offset:2048
	ds_read_b128 v[98:101], v96 offset:3072
.LBB0_1021:
	s_add_i32 vcc_hi, s46, 2
	s_add_u32 s84, s44, 0x80
	s_addc_u32 s47, s45, 0
	s_add_i32 s29, 0, 0x10000
	v_add_u32_e32 v96, s29, v225
	ds_read_b128 v[56:59], v96
	ds_read_b128 v[68:71], v96 offset:1024
	s_cmp_eq_u32 s90, s46
	s_cselect_b32 s46, s80, s84
	s_cselect_b32 s47, s81, s47
	s_cselect_b32 s85, s83, vcc_lo
	s_cselect_b32 s84, s82, s87
	s_add_i32 m0, s2, 0xc000
	ds_read_b128 v[102:105], v227
	ds_read_b128 v[112:115], v227 offset:1024
	ds_read_b128 v[124:127], v227 offset:2048
	ds_read_b128 v[192:195], v227 offset:3072
	ds_read_b128 v[196:199], v227 offset:4096
	ds_read_b128 v[200:203], v227 offset:5120
	global_load_lds_dwordx4 v188, s[44:45]
	s_add_i32 m0, s2, 0xe000
	s_mov_b64 exec, s[98:99]
	global_load_lds_dwordx4 v190, s[44:45]
	s_mov_b64 exec, -1
	s_waitcnt lgkmcnt(6)
	s_setprio 1
	s_barrier
	s_waitcnt lgkmcnt(0)
	v_mfma_f32_16x16x32_bf16 v[172:175], v[56:59], v[102:105], v[172:175]
	v_mfma_f32_16x16x32_bf16 v[168:171], v[80:83], v[102:105], v[168:171]
	v_mfma_f32_16x16x32_bf16 v[156:159], v[56:59], v[124:127], v[156:159]
	v_mfma_f32_16x16x32_bf16 v[152:155], v[80:83], v[124:127], v[152:155]
	v_mfma_f32_16x16x32_bf16 v[132:135], v[56:59], v[196:199], v[132:135]
	v_mfma_f32_16x16x32_bf16 v[128:131], v[80:83], v[196:199], v[128:131]
	v_mfma_f32_16x16x32_bf16 v[172:175], v[68:71], v[112:115], v[172:175]
	v_mfma_f32_16x16x32_bf16 v[168:171], v[98:101], v[112:115], v[168:171]
	v_mfma_f32_16x16x32_bf16 v[156:159], v[68:71], v[192:195], v[156:159]
	v_mfma_f32_16x16x32_bf16 v[152:155], v[98:101], v[192:195], v[152:155]
	v_mfma_f32_16x16x32_bf16 v[132:135], v[68:71], v[200:203], v[132:135]
	v_mfma_f32_16x16x32_bf16 v[128:131], v[98:101], v[200:203], v[128:131]
	s_barrier
	s_setprio 0
	s_add_i32 s96, 0, 0x14000
	s_add_i32 s29, s29, s18
	v_add_u32_e32 v96, s96, v225
	v_lshl_add_u64 v[106:107], s[84:85], 0, v[182:183]
	s_mov_b32 m0, s29
	ds_read_b128 v[228:231], v96
	ds_read_b128 v[232:235], v96 offset:1024
	ds_read_b128 v[236:239], v96 offset:2048
	ds_read_b128 v[240:243], v96 offset:3072
	global_load_lds_dwordx4 v182, s[84:85]
	v_lshl_add_u64 v[248:249], s[84:85], 0, v[186:187]
	s_add_i32 m0, s29, 0x2000
	s_nop 0
	global_load_lds_dwordx4 v186, s[84:85]
	s_setprio 1
	s_barrier
	s_waitcnt lgkmcnt(0)
	v_mfma_f32_16x16x32_bf16 v[164:167], v[228:231], v[102:105], v[164:167]
	v_mfma_f32_16x16x32_bf16 v[102:105], v[236:239], v[102:105], v[160:163]
	v_mfma_f32_16x16x32_bf16 v[120:123], v[228:231], v[196:199], v[120:123]
	s_mov_b32 m0, s2
	v_mfma_f32_16x16x32_bf16 v[116:119], v[236:239], v[196:199], v[116:119]
	v_lshl_add_u64 v[250:251], s[46:47], 0, v[176:177]
	v_mfma_f32_16x16x32_bf16 v[164:167], v[232:235], v[112:115], v[164:167]
	v_mfma_f32_16x16x32_bf16 v[102:105], v[240:243], v[112:115], v[102:105]
	v_mfma_f32_16x16x32_bf16 v[112:115], v[228:231], v[124:127], v[148:151]
	v_mfma_f32_16x16x32_bf16 v[124:127], v[236:239], v[124:127], v[144:147]
	v_mfma_f32_16x16x32_bf16 v[120:123], v[232:235], v[200:203], v[120:123]
	v_mfma_f32_16x16x32_bf16 v[116:119], v[240:243], v[200:203], v[116:119]
	v_mfma_f32_16x16x32_bf16 v[112:115], v[232:235], v[192:195], v[112:115]
	v_mfma_f32_16x16x32_bf16 v[124:127], v[240:243], v[192:195], v[124:127]
	s_barrier
	s_setprio 0
	ds_read_b128 v[144:147], v227 offset:16384
	ds_read_b128 v[148:151], v227 offset:17408
	ds_read_b128 v[160:163], v227 offset:18432
	ds_read_b128 v[192:195], v227 offset:19456
	ds_read_b128 v[196:199], v227 offset:20480
	ds_read_b128 v[200:203], v227 offset:21504
	global_load_lds_dwordx4 v176, s[46:47]
	v_lshl_add_u64 v[252:253], s[46:47], 0, v[184:185]
	s_mov_b32 m0, s3
	s_mov_b64 exec, s[98:99]
	global_load_lds_dwordx4 v184, s[46:47]
	s_mov_b64 exec, -1
	s_waitcnt vmcnt(10)
	s_setprio 1
	s_barrier
	s_waitcnt lgkmcnt(0)
	v_mfma_f32_16x16x32_bf16 v[88:91], v[56:59], v[144:147], v[88:91]
	v_mfma_f32_16x16x32_bf16 v[84:87], v[80:83], v[144:147], v[84:87]
	v_mfma_f32_16x16x32_bf16 v[52:55], v[56:59], v[160:163], v[52:55]
	v_mfma_f32_16x16x32_bf16 v[48:51], v[80:83], v[160:163], v[48:51]
	v_mfma_f32_16x16x32_bf16 v[28:31], v[56:59], v[196:199], v[28:31]
	v_mfma_f32_16x16x32_bf16 v[24:27], v[80:83], v[196:199], v[24:27]
	v_mfma_f32_16x16x32_bf16 v[88:91], v[68:71], v[148:151], v[88:91]
	v_mfma_f32_16x16x32_bf16 v[84:87], v[98:101], v[148:151], v[84:87]
	v_mfma_f32_16x16x32_bf16 v[52:55], v[68:71], v[192:195], v[52:55]
	v_mfma_f32_16x16x32_bf16 v[48:51], v[98:101], v[192:195], v[48:51]
	v_mfma_f32_16x16x32_bf16 v[28:31], v[68:71], v[200:203], v[28:31]
	v_mfma_f32_16x16x32_bf16 v[24:27], v[98:101], v[200:203], v[24:27]
	s_barrier
	s_setprio 0
	v_add_u32_e32 v96, 0x18000, v225
	ds_read_b128 v[80:83], v96 offset:2048
	ds_read_b128 v[98:101], v96 offset:3072
	s_add_u32 s84, s84, s57
	s_addc_u32 s85, s85, 0
	s_add_i32 s29, s96, s18
	v_lshl_add_u64 v[218:219], s[84:85], 0, v[182:183]
	s_mov_b32 m0, s29
	v_lshl_add_u64 v[220:221], s[84:85], 0, v[186:187]
	global_load_lds_dwordx4 v182, s[84:85]
	s_add_i32 m0, s29, 0x2000
	s_nop 0
	global_load_lds_dwordx4 v186, s[84:85]
	s_waitcnt vmcnt(6)
	s_setprio 1
	s_barrier
	v_mfma_f32_16x16x32_bf16 v[44:47], v[228:231], v[160:163], v[44:47]
	v_mfma_f32_16x16x32_bf16 v[40:43], v[236:239], v[160:163], v[40:43]
	v_mfma_f32_16x16x32_bf16 v[20:23], v[228:231], v[196:199], v[20:23]
	s_add_i32 s29, 0, 0x18000
	v_mfma_f32_16x16x32_bf16 v[16:19], v[236:239], v[196:199], v[16:19]
	v_add_u32_e32 v96, s29, v225
	v_mfma_f32_16x16x32_bf16 v[56:59], v[228:231], v[144:147], v[76:79]
	v_mfma_f32_16x16x32_bf16 v[68:71], v[236:239], v[144:147], v[72:75]
	v_mfma_f32_16x16x32_bf16 v[44:47], v[232:235], v[192:195], v[44:47]
	v_mfma_f32_16x16x32_bf16 v[40:43], v[240:243], v[192:195], v[40:43]
	v_mfma_f32_16x16x32_bf16 v[20:23], v[232:235], v[200:203], v[20:23]
	v_mfma_f32_16x16x32_bf16 v[16:19], v[240:243], v[200:203], v[16:19]
	v_mfma_f32_16x16x32_bf16 v[56:59], v[232:235], v[148:151], v[56:59]
	v_mfma_f32_16x16x32_bf16 v[68:71], v[240:243], v[148:151], v[68:71]
	s_barrier
	s_setprio 0
	ds_read_b128 v[72:75], v96
	ds_read_b128 v[76:79], v96 offset:1024
	s_add_u32 s46, s46, s64
	s_addc_u32 s47, s47, 0
	s_mov_b32 m0, s4
	ds_read_b128 v[144:147], v227 offset:32768
	ds_read_b128 v[148:151], v227 offset:33792
	ds_read_b128 v[192:195], v227 offset:34816
	ds_read_b128 v[196:199], v227 offset:35840
	ds_read_b128 v[200:203], v227 offset:36864
	ds_read_b128 v[228:231], v227 offset:37888
	global_load_lds_dwordx4 v176, s[46:47]
	s_mov_b32 m0, s5
	s_mov_b64 exec, s[98:99]
	global_load_lds_dwordx4 v184, s[46:47]
	s_mov_b64 exec, -1
	s_waitcnt lgkmcnt(6)
	s_setprio 1
	s_barrier
	s_waitcnt lgkmcnt(0)
	v_mfma_f32_16x16x32_bf16 v[160:163], v[72:75], v[144:147], v[172:175]
	v_mfma_f32_16x16x32_bf16 v[172:175], v[76:79], v[148:151], v[160:163]
	v_mfma_f32_16x16x32_bf16 v[160:163], v[80:83], v[144:147], v[168:171]
	v_mfma_f32_16x16x32_bf16 v[156:159], v[72:75], v[192:195], v[156:159]
	v_mfma_f32_16x16x32_bf16 v[152:155], v[80:83], v[192:195], v[152:155]
	v_mfma_f32_16x16x32_bf16 v[132:135], v[72:75], v[200:203], v[132:135]
	v_mfma_f32_16x16x32_bf16 v[128:131], v[80:83], v[200:203], v[128:131]
	v_mfma_f32_16x16x32_bf16 v[168:171], v[98:101], v[148:151], v[160:163]
	v_mfma_f32_16x16x32_bf16 v[156:159], v[76:79], v[196:199], v[156:159]
	v_mfma_f32_16x16x32_bf16 v[152:155], v[98:101], v[196:199], v[152:155]
	v_mfma_f32_16x16x32_bf16 v[132:135], v[76:79], v[228:231], v[132:135]
	v_mfma_f32_16x16x32_bf16 v[128:131], v[98:101], v[228:231], v[128:131]
	s_barrier
	s_setprio 0
	s_add_i32 s46, 0, 0x1c000
	s_add_i32 s29, s29, s18
	v_add_u32_e32 v96, s46, v225
	v_lshl_add_u64 v[106:107], v[106:107], 0, s[6:7]
	s_mov_b32 m0, s29
	ds_read_b128 v[232:235], v96
	ds_read_b128 v[236:239], v96 offset:1024
	ds_read_b128 v[240:243], v96 offset:2048
	ds_read_b128 v[244:247], v96 offset:3072
	global_load_lds_dwordx4 v[106:107], off
	v_lshl_add_u64 v[106:107], v[248:249], 0, s[6:7]
	s_add_i32 m0, s29, 0x2000
	s_nop 0
	global_load_lds_dwordx4 v[106:107], off
	s_setprio 1
	s_barrier
	s_waitcnt lgkmcnt(0)
	v_mfma_f32_16x16x32_bf16 v[160:163], v[232:235], v[144:147], v[164:167]
	v_mfma_f32_16x16x32_bf16 v[102:105], v[240:243], v[144:147], v[102:105]
	v_mfma_f32_16x16x32_bf16 v[164:167], v[236:239], v[148:151], v[160:163]
	s_mov_b32 m0, s88
	v_mfma_f32_16x16x32_bf16 v[160:163], v[244:247], v[148:151], v[102:105]
	v_lshl_add_u64 v[106:107], v[250:251], 0, s[6:7]
	v_mfma_f32_16x16x32_bf16 v[102:105], v[232:235], v[192:195], v[112:115]
	v_mfma_f32_16x16x32_bf16 v[148:151], v[236:239], v[196:199], v[102:105]
	v_mfma_f32_16x16x32_bf16 v[102:105], v[240:243], v[192:195], v[124:127]
	v_mfma_f32_16x16x32_bf16 v[144:147], v[244:247], v[196:199], v[102:105]
	v_mfma_f32_16x16x32_bf16 v[102:105], v[232:235], v[200:203], v[120:123]
	v_mfma_f32_16x16x32_bf16 v[120:123], v[236:239], v[228:231], v[102:105]
	v_mfma_f32_16x16x32_bf16 v[102:105], v[240:243], v[200:203], v[116:119]
	v_mfma_f32_16x16x32_bf16 v[116:119], v[244:247], v[228:231], v[102:105]
	s_barrier
	s_setprio 0
	s_nop 2
	ds_read_b128 v[102:105], v227 offset:49152
	ds_read_b128 v[112:115], v227 offset:50176
	ds_read_b128 v[124:127], v227 offset:51200
	ds_read_b128 v[192:195], v227 offset:52224
	ds_read_b128 v[196:199], v227 offset:53248
	ds_read_b128 v[200:203], v227 offset:54272
	global_load_lds_dwordx4 v[106:107], off
	v_lshl_add_u64 v[106:107], v[252:253], 0, s[6:7]
	s_mov_b32 m0, s89
	s_mov_b64 exec, s[98:99]
	global_load_lds_dwordx4 v[106:107], off
	s_mov_b64 exec, -1
	s_waitcnt vmcnt(10)
	s_setprio 1
	s_barrier
	s_waitcnt lgkmcnt(0)
	v_mfma_f32_16x16x32_bf16 v[88:91], v[72:75], v[102:105], v[88:91]
	v_mfma_f32_16x16x32_bf16 v[84:87], v[80:83], v[102:105], v[84:87]
	v_mfma_f32_16x16x32_bf16 v[52:55], v[72:75], v[124:127], v[52:55]
	v_mfma_f32_16x16x32_bf16 v[48:51], v[80:83], v[124:127], v[48:51]
	v_mfma_f32_16x16x32_bf16 v[28:31], v[72:75], v[196:199], v[28:31]
	v_mfma_f32_16x16x32_bf16 v[24:27], v[80:83], v[196:199], v[24:27]
	v_mfma_f32_16x16x32_bf16 v[88:91], v[76:79], v[112:115], v[88:91]
	v_mfma_f32_16x16x32_bf16 v[84:87], v[98:101], v[112:115], v[84:87]
	v_mfma_f32_16x16x32_bf16 v[52:55], v[76:79], v[192:195], v[52:55]
	v_mfma_f32_16x16x32_bf16 v[48:51], v[98:101], v[192:195], v[48:51]
	v_mfma_f32_16x16x32_bf16 v[28:31], v[76:79], v[200:203], v[28:31]
	v_mfma_f32_16x16x32_bf16 v[24:27], v[98:101], v[200:203], v[24:27]
	s_barrier
	s_setprio 0
	v_add_u32_e32 v96, 0x10000, v225
	ds_read_b128 v[80:83], v96 offset:2048
	ds_read_b128 v[98:101], v96 offset:3072
	s_add_i32 s29, s46, s18
	v_lshl_add_u64 v[72:73], v[218:219], 0, s[6:7]
	s_mov_b32 m0, s29
	s_nop 0
	global_load_lds_dwordx4 v[72:73], off
	v_lshl_add_u64 v[72:73], v[220:221], 0, s[6:7]
	s_add_i32 m0, s29, 0x2000
	s_nop 0
	global_load_lds_dwordx4 v[72:73], off
	s_waitcnt vmcnt(6)
	s_setprio 1
	s_barrier
	v_mfma_f32_16x16x32_bf16 v[56:59], v[232:235], v[102:105], v[56:59]
	v_mfma_f32_16x16x32_bf16 v[76:79], v[236:239], v[112:115], v[56:59]
	v_mfma_f32_16x16x32_bf16 v[56:59], v[240:243], v[102:105], v[68:71]
	s_add_u32 s44, s44, 0x100
	v_mfma_f32_16x16x32_bf16 v[44:47], v[232:235], v[124:127], v[44:47]
	s_addc_u32 s45, s45, 0
	v_mfma_f32_16x16x32_bf16 v[40:43], v[240:243], v[124:127], v[40:43]
	s_add_u32 s87, s87, 0x100
	v_mfma_f32_16x16x32_bf16 v[20:23], v[232:235], v[196:199], v[20:23]
	s_addc_u32 vcc_lo, vcc_lo, 0
	v_mfma_f32_16x16x32_bf16 v[16:19], v[240:243], v[196:199], v[16:19]
	s_cmp_ge_u32 vcc_hi, s37
	v_mfma_f32_16x16x32_bf16 v[72:75], v[244:247], v[112:115], v[56:59]
	s_mov_b32 s46, vcc_hi
	v_mfma_f32_16x16x32_bf16 v[44:47], v[236:239], v[192:195], v[44:47]
	v_mfma_f32_16x16x32_bf16 v[40:43], v[244:247], v[192:195], v[40:43]
	v_mfma_f32_16x16x32_bf16 v[20:23], v[236:239], v[200:203], v[20:23]
	v_mfma_f32_16x16x32_bf16 v[16:19], v[244:247], v[200:203], v[16:19]
	s_barrier
	s_setprio 0
	s_cbranch_scc0 .LBB0_1021
	s_waitcnt lgkmcnt(0)
	s_mul_i32 s44, s86, 0xc0
	s_add_i32 s44, s44, s19
	s_cmpk_lt_u32 s44, 0x2000
	v_or_b32_e32 v198, s44, v223
	s_cselect_b32 s44, 1, 2
	v_mov_b32_e32 v56, s44
	v_cmp_lt_i32_e32 vcc, s23, v198
	v_lshl_or_b32 v192, s72, 8, v226
	v_ashrrev_i32_e32 v193, 31, v192
	v_cndmask_b32_e32 v228, 0, v56, vcc
	v_mul_u32_u24_e32 v56, 0x1800, v228
	v_lshlrev_b32_e32 v96, 2, v56
	v_lshl_add_u64 v[56:57], s[70:71], 0, v[96:97]
	v_lshlrev_b64 v[68:69], 2, v[192:193]
	v_lshl_add_u64 v[124:125], v[56:57], 0, v[68:69]
	global_load_dwordx4 v[56:59], v[124:125], off
	v_cndmask_b32_e64 v70, 0, 1, s[78:79]
	v_cmp_ne_u32_e64 s[46:47], 1, v70
	s_andn2_b64 vcc, exec, s[78:79]
	v_lshl_add_u64 v[196:197], s[54:55], 0, v[68:69]
	s_cbranch_vccnz .LBB0_1024
	global_load_dwordx4 v[80:83], v[196:197], off
	s_waitcnt vmcnt(0)
	v_pk_mul_f32 v[58:59], v[58:59], v[82:83]
	v_pk_mul_f32 v[56:57], v[56:57], v[80:81]
